# v088 plus cross-item prefetch in sliding-window attention: the next item's 16 K/V staging loads are issued during the current item's QK section
# baseline (speedup 1.0000x reference)
; __device__ __forceinline__ int ptid_(int wave) { int l_; asm volatile("v_mbcnt_lo_u32_b32 %0, -1, 0\n\tv_mbcnt_hi_u32_b32 %0, -1, %0" : "=v"(l_)); return (wave << 6) | l_; }
; __device__ void swa_item(const Params& p, int item) {
;   float* misc = (float*)(p.ws + MISC_OFF);
;   bfu* buf = (bfu*)(p.ws + R_OFF);
;   const int pat = item >> 10; const int rem = item & 1023;
;   const int b = rem >> 7, head = (rem >> 5) & 3, sub = rem & 31;
;   const int dil = (pat == 0) ? 1 : (pat == 1 ? 4 : 16);
;   const int nqb = 32 / dil;
;   const int r = sub / nqb, qb = sub % nqb;
;   int tid = ptid_(p.tid); asm volatile("" : "+v"(tid)); const int w = tid >> 6, lane = tid & 63, c = lane & 15, q = lane >> 4;
;   bfu* Vt = (bfu*)smem;
;   bfu* Ks = Vt + 128 * 280;
;   bfu* Pl = Ks + w * (16 * 168);
;   const long rowb = (long)b * TSEQ;
;   const int qcol = pat * 512 + head * 128, kcol = 1536 + qcol, vcol = 3072 + qcol;
;   __syncthreads();
;   _Pragma("unroll") for (int i = 0; i < 4; ++i) {
;     int co = tid + 512 * i; int c8 = co & 15, kp = co >> 4;
;     int j0 = qb * 128 - 128 + 2 * kp;
;     const int j0c = (j0 >= 0) ? j0 : 0;
;     bf16x8 v0 = *(const bf16x8*)(buf + (rowb + (long)j0c * dil + r) * 4608 + vcol + c8 * 8);
;     bf16x8 v1 = *(const bf16x8*)(buf + (rowb + (long)(j0c + 1) * dil + r) * 4608 + vcol + c8 * 8);
;     if (j0 < 0) { v0 = (bf16x8){0, 0, 0, 0, 0, 0, 0, 0}; v1 = v0; }
;     const int chs = ((kp >> 2) ^ c8) * 8 + ((2 * kp) & 7);
;     _Pragma("unroll") for (int e = 0; e < 8; ++e)
;       *(unsigned*)(Vt + (c8 * 8 + e) * 280 + chs) = (unsigned)(bfu)v0[e] | ((unsigned)(bfu)v1[e] << 16);
;   }
;   _Pragma("unroll") for (int i = 0; i < 8; ++i) {
;     int co = tid + 512 * i; int c8 = co & 15, kj = co >> 4;
;     int j = qb * 128 - 128 + kj; j = (j >= 0) ? j : 0;
;     *(bf16x8*)(Ks + kj * 136 + c8 * 8) = *(const bf16x8*)(buf + (rowb + (long)j * dil + r) * 4608 + kcol + c8 * 8);
.LBB0_102:
	s_cmpk_gt_i32 s21, 0xbff
	s_cbranch_scc1 .LBB0_113
	s_ashr_i32 s88, s21, 10
	s_bfe_u32 s23, s21, 0x20005
	s_and_b32 s0, s21, 31
	s_cmp_eq_u32 s88, 1
	s_cselect_b32 s1, 2, 4
	s_cmpk_gt_u32 s21, 0x3ff
	s_cselect_b32 s22, s1, 0
	s_lshr_b32 s1, 32, s22
	s_sub_i32 s2, 5, s22
	s_add_i32 s1, s1, -1
	s_lshr_b32 s2, s0, s2
	s_and_b32 s34, s1, s0
	s_lshl_b32 s0, s21, 5
	s_and_b32 s1, s0, 0x7000
	s_lshl_b32 s0, s88, 9
	s_lshl_b32 s3, s23, 7
	s_or_b32 s0, s3, s0
	v_readlane_b32 s18, v254, 13
	s_lshl_b32 s35, s34, 7
	s_or_b32 s18, s2, s1
	s_ashr_i32 s1, s0, 31
	v_mbcnt_lo_u32_b32 v0, -1, 0
	v_mbcnt_hi_u32_b32 v0, -1, v0
	s_add_i32 s12, s35, 0xffffff80
	v_or_b32_e32 v50, s33, v0
	s_lshl_b64 s[2:3], s[0:1], 1
	s_add_u32 s52, s16, s2
	v_and_b32_e32 v55, 15, v50
	s_addc_u32 s53, s17, s3
	v_lshlrev_b32_e32 v0, 4, v55
	v_ashrrev_i32_e32 v13, 3, v50
	s_waitcnt lgkmcnt(0)
	v_lshl_add_u64 v[2:3], s[52:53], 0, v[0:1]
	v_and_b32_e32 v0, -2, v13
	v_add_u32_e32 v14, s12, v0
	s_mov_b64 s[2:3], 0x1800
	v_max_i32_e32 v0, 0, v14
	v_lshl_add_u64 v[10:11], v[2:3], 0, s[2:3]
	v_lshlrev_b64 v[2:3], s22, v[0:1]
	v_or_b32_e32 v0, 1, v0
	v_readlane_b32 s19, v254, 14
	v_lshlrev_b64 v[6:7], s22, v[0:1]
	s_nop 0
	v_lshl_add_u64 v[2:3], v[2:3], 0, s[18:19]
	v_lshl_add_u64 v[6:7], v[6:7], 0, s[18:19]
	v_mad_u64_u32 v[4:5], s[2:3], v2, s89, v[10:11]
	v_mad_u64_u32 v[8:9], s[2:3], v6, s89, v[10:11]
	v_mad_u32_u24 v5, v3, s89, v5
	v_mad_u32_u24 v9, v7, s89, v9
	s_barrier
	s_cmpk_ge_u32 s21, 0x100
	s_cbranch_scc1 .Lswa_have_kv
	v_lshlrev_b32_e32 v140, 4, v55
	v_mov_b32_e32 v141, 0
	v_lshl_add_u64 v[140:141], s[52:53], 0, v[140:141]
	s_mov_b64 s[2:3], 0x1800
	v_lshl_add_u64 v[142:143], v[140:141], 0, s[2:3]
	v_lshrrev_b32_e32 v144, 4, v50
	v_lshl_add_u32 v145, v144, 1, s12
	v_max_i32_e32 v146, 0, v145
	v_lshlrev_b32_e32 v147, s22, v146
	v_add_u32_e32 v147, s18, v147
	v_mad_u64_u32 v[148:149], vcc, v147, s89, v[142:143]
	global_load_dwordx4 v[76:79], v[148:149], off
	v_or_b32_e32 v146, 1, v146
	v_lshlrev_b32_e32 v147, s22, v146
	v_add_u32_e32 v147, s18, v147
	v_mad_u64_u32 v[148:149], vcc, v147, s89, v[142:143]
	global_load_dwordx4 v[80:83], v[148:149], off
	v_add_u32_e32 v146, 64, v145
	v_max_i32_e32 v146, 0, v146
	v_lshlrev_b32_e32 v147, s22, v146
	v_add_u32_e32 v147, s18, v147
	v_mad_u64_u32 v[148:149], vcc, v147, s89, v[142:143]
	global_load_dwordx4 v[84:87], v[148:149], off
	v_or_b32_e32 v146, 1, v146
	v_lshlrev_b32_e32 v147, s22, v146
	v_add_u32_e32 v147, s18, v147
	v_mad_u64_u32 v[148:149], vcc, v147, s89, v[142:143]
	global_load_dwordx4 v[88:91], v[148:149], off
	v_add_u32_e32 v146, 128, v145
	v_max_i32_e32 v146, 0, v146
	v_lshlrev_b32_e32 v147, s22, v146
	v_add_u32_e32 v147, s18, v147
	v_mad_u64_u32 v[148:149], vcc, v147, s89, v[142:143]
	global_load_dwordx4 v[92:95], v[148:149], off
	v_or_b32_e32 v146, 1, v146
	v_lshlrev_b32_e32 v147, s22, v146
	v_add_u32_e32 v147, s18, v147
	v_mad_u64_u32 v[148:149], vcc, v147, s89, v[142:143]
	global_load_dwordx4 v[96:99], v[148:149], off
	v_add_u32_e32 v146, 192, v145
	v_max_i32_e32 v146, 0, v146
	v_lshlrev_b32_e32 v147, s22, v146
	v_add_u32_e32 v147, s18, v147
	v_mad_u64_u32 v[148:149], vcc, v147, s89, v[142:143]
	global_load_dwordx4 v[100:103], v[148:149], off
	v_or_b32_e32 v146, 1, v146
	v_lshlrev_b32_e32 v147, s22, v146
	v_add_u32_e32 v147, s18, v147
	v_mad_u64_u32 v[148:149], vcc, v147, s89, v[142:143]
	global_load_dwordx4 v[104:107], v[148:149], off
	v_add_u32_e32 v145, s12, v144
	v_max_i32_e32 v146, 0, v145
	v_lshlrev_b32_e32 v147, s22, v146
	v_add_u32_e32 v147, s18, v147
	v_mad_u64_u32 v[148:149], vcc, v147, s89, v[140:141]
	global_load_dwordx4 v[108:111], v[148:149], off offset:3072
	v_add_u32_e32 v146, 32, v145
	v_max_i32_e32 v146, 0, v146
	v_lshlrev_b32_e32 v147, s22, v146
	v_add_u32_e32 v147, s18, v147
	v_mad_u64_u32 v[148:149], vcc, v147, s89, v[140:141]
	global_load_dwordx4 v[112:115], v[148:149], off offset:3072
	v_add_u32_e32 v146, 64, v145
	v_max_i32_e32 v146, 0, v146
	v_lshlrev_b32_e32 v147, s22, v146
	v_add_u32_e32 v147, s18, v147
	v_mad_u64_u32 v[148:149], vcc, v147, s89, v[140:141]
	global_load_dwordx4 v[116:119], v[148:149], off offset:3072
	v_add_u32_e32 v146, 96, v145
	v_max_i32_e32 v146, 0, v146
	v_lshlrev_b32_e32 v147, s22, v146
	v_add_u32_e32 v147, s18, v147
	v_mad_u64_u32 v[148:149], vcc, v147, s89, v[140:141]
	global_load_dwordx4 v[120:123], v[148:149], off offset:3072
	v_add_u32_e32 v146, 128, v145
	v_max_i32_e32 v146, 0, v146
	v_lshlrev_b32_e32 v147, s22, v146
	v_add_u32_e32 v147, s18, v147
	v_mad_u64_u32 v[148:149], vcc, v147, s89, v[140:141]
	global_load_dwordx4 v[124:127], v[148:149], off offset:3072
	v_add_u32_e32 v146, 160, v145
	v_max_i32_e32 v146, 0, v146
	v_lshlrev_b32_e32 v147, s22, v146
	v_add_u32_e32 v147, s18, v147
	v_mad_u64_u32 v[148:149], vcc, v147, s89, v[140:141]
	global_load_dwordx4 v[128:131], v[148:149], off offset:3072
	v_add_u32_e32 v146, 192, v145
	v_max_i32_e32 v146, 0, v146
	v_lshlrev_b32_e32 v147, s22, v146
	v_add_u32_e32 v147, s18, v147
	v_mad_u64_u32 v[148:149], vcc, v147, s89, v[140:141]
	global_load_dwordx4 v[132:135], v[148:149], off offset:3072
	v_add_u32_e32 v146, 224, v145
	v_max_i32_e32 v146, 0, v146
	v_lshlrev_b32_e32 v147, s22, v146
	v_add_u32_e32 v147, s18, v147
	v_mad_u64_u32 v[148:149], vcc, v147, s89, v[140:141]
	global_load_dwordx4 v[136:139], v[148:149], off offset:3072
; __device__ void swa_item(const Params& p, int item) {
;     ...
;   _Pragma("unroll") for (int i = 0; i < 4; ++i) {
;     int co = tid + 512 * i; int c8 = co & 15, kp = co >> 4;
;     int j0 = qb * 128 - 128 + 2 * kp;
;     const int j0c = (j0 >= 0) ? j0 : 0;
;     bf16x8 v0 = *(const bf16x8*)(buf + (rowb + (long)j0c * dil + r) * 4608 + vcol + c8 * 8);
;     bf16x8 v1 = *(const bf16x8*)(buf + (rowb + (long)(j0c + 1) * dil + r) * 4608 + vcol + c8 * 8);
;     if (j0 < 0) { v0 = (bf16x8){0, 0, 0, 0, 0, 0, 0, 0}; v1 = v0; }
;     const int chs = ((kp >> 2) ^ c8) * 8 + ((2 * kp) & 7);
;     _Pragma("unroll") for (int e = 0; e < 8; ++e)
;       *(unsigned*)(Vt + (c8 * 8 + e) * 280 + chs) = (unsigned)(bfu)v0[e] | ((unsigned)(bfu)v1[e] << 16);
;   }
.Lswa_have_kv:
	v_mov_b32_e32 v243, s18
	v_lshrrev_b32_e32 v243, 12, v243
	v_add_u32_e32 v243, 2, v243
	v_lshrrev_b32_e32 v243, 3, v243
	v_sub_u32_e32 v243, 1, v243
	v_lshlrev_b32_e32 v243, 13, v243
	v_add_u32_e32 v243, s18, v243
	v_lshrrev_b32_e32 v244, 1, v50
	v_and_b32_e32 v245, 1, v50
	v_add_u32_e32 v246, s12, v244
	v_max_i32_e32 v246, 0, v246
	v_lshlrev_b32_e32 v246, s22, v246
	v_add_u32_e32 v246, v243, v246
	v_mul_u32_u24_e32 v246, 0x2400, v246
	v_lshl_add_u32 v246, v245, 7, v246
	v_add_u32_e32 v240, 0xc00, v246
	v_add_u32_e32 v241, 0x1800, v246
	v_and_b32_e32 v244, 0x7f, v244
	v_add_u32_e32 v244, s35, v244
	v_lshlrev_b32_e32 v244, s22, v244
	v_add_u32_e32 v244, v243, v244
	v_mul_u32_u24_e32 v244, 0x2400, v244
	v_lshl_add_u32 v242, v245, 7, v244
	s_waitcnt vmcnt(14)
	v_mov_b64_e32 v[2:3], v[76:77]
	v_mov_b64_e32 v[4:5], v[78:79]
	v_ashrrev_i32_e32 v12, 6, v50
	v_mov_b64_e32 v[6:7], v[80:81]
	v_mov_b64_e32 v[8:9], v[82:83]
	v_cmp_gt_i32_e32 vcc, 0, v14
	v_lshlrev_b32_e32 v13, 1, v13
	v_and_b32_e32 v14, 12, v13
	s_mov_b32 s13, 0x1000504
	v_mul_u32_u24_e32 v13, 0x1180, v55
	s_mov_b32 s14, 0x3020706
	v_add_u32_e32 v51, 0x200, v50
	v_cndmask_b32_e64 v2, v2, 0, vcc
	v_cndmask_b32_e64 v3, v3, 0, vcc
	v_cndmask_b32_e64 v0, v9, 0, vcc
	v_bitop3_b32 v9, v12, v50, 15 bitop3:0x78
	v_cndmask_b32_e64 v6, v6, 0, vcc
	v_lshl_add_u32 v9, v9, 4, 0
	v_cndmask_b32_e64 v7, v7, 0, vcc
	v_perm_b32 v15, v2, v6, s13
	v_add3_u32 v9, v9, v14, v13
	v_perm_b32 v2, v2, v6, s14
	v_cndmask_b32_e64 v8, v8, 0, vcc
	v_cndmask_b32_e64 v4, v4, 0, vcc
	ds_write2_b32 v9, v15, v2 offset1:140
	v_perm_b32 v2, v3, v7, s13
	v_perm_b32 v3, v3, v7, s14
	v_add_u32_e32 v6, 0x400, v9
	v_cndmask_b32_e64 v5, v5, 0, vcc
	ds_write2_b32 v6, v2, v3 offset0:24 offset1:164
	v_perm_b32 v2, v4, v8, s13
	v_perm_b32 v3, v4, v8, s14
	v_add_u32_e32 v4, 0x800, v9
	ds_write2_b32 v4, v2, v3 offset0:48 offset1:188
	v_perm_b32 v2, v5, v0, s13
	v_perm_b32 v0, v5, v0, s14
	v_add_u32_e32 v3, 0xc00, v9
	v_ashrrev_i32_e32 v14, 3, v51
	ds_write2_b32 v3, v2, v0 offset0:72 offset1:212
	v_and_b32_e32 v0, -2, v14
	v_add_u32_e32 v15, s12, v0
	v_max_i32_e32 v0, 0, v15
	v_lshlrev_b64 v[2:3], s22, v[0:1]
	v_or_b32_e32 v0, 1, v0
	v_lshlrev_b64 v[6:7], s22, v[0:1]
	v_lshl_add_u64 v[2:3], v[2:3], 0, s[18:19]
	v_lshl_add_u64 v[6:7], v[6:7], 0, s[18:19]
	v_mad_u64_u32 v[4:5], s[2:3], v2, s89, v[10:11]
	v_mad_u64_u32 v[8:9], s[2:3], v6, s89, v[10:11]
	v_mad_u32_u24 v5, v3, s89, v5
	v_mad_u32_u24 v9, v7, s89, v9
	s_waitcnt vmcnt(12)
	v_mov_b64_e32 v[2:3], v[84:85]
	v_mov_b64_e32 v[4:5], v[86:87]
	v_cmp_gt_i32_e32 vcc, 0, v15
	v_mov_b64_e32 v[6:7], v[88:89]
	v_mov_b64_e32 v[8:9], v[90:91]
	v_lshlrev_b32_e32 v14, 1, v14
	v_and_b32_e32 v14, 12, v14
	v_cndmask_b32_e64 v2, v2, 0, vcc
	v_cndmask_b32_e64 v3, v3, 0, vcc
	v_cndmask_b32_e64 v0, v9, 0, vcc
	v_ashrrev_i32_e32 v9, 6, v51
	v_bitop3_b32 v9, v9, v50, 15 bitop3:0x78
	v_cndmask_b32_e64 v6, v6, 0, vcc
	v_lshl_add_u32 v9, v9, 4, 0
	v_cndmask_b32_e64 v7, v7, 0, vcc
	v_perm_b32 v15, v2, v6, s13
	v_add3_u32 v9, v9, v14, v13
	v_perm_b32 v2, v2, v6, s14
	v_cndmask_b32_e64 v8, v8, 0, vcc
	v_cndmask_b32_e64 v4, v4, 0, vcc
	ds_write2_b32 v9, v15, v2 offset1:140
	v_perm_b32 v2, v3, v7, s13
	v_perm_b32 v3, v3, v7, s14
	v_add_u32_e32 v6, 0x400, v9
	v_cndmask_b32_e64 v5, v5, 0, vcc
	ds_write2_b32 v6, v2, v3 offset0:24 offset1:164
	v_perm_b32 v2, v4, v8, s13
	v_perm_b32 v3, v4, v8, s14
	v_add_u32_e32 v4, 0x800, v9
	v_add_u32_e32 v14, 0x400, v50
	ds_write2_b32 v4, v2, v3 offset0:48 offset1:188
	v_perm_b32 v2, v5, v0, s13
	v_perm_b32 v0, v5, v0, s14
	v_add_u32_e32 v3, 0xc00, v9
	v_ashrrev_i32_e32 v15, 3, v14
	ds_write2_b32 v3, v2, v0 offset0:72 offset1:212
	v_and_b32_e32 v0, -2, v15
	v_add_u32_e32 v16, s12, v0
	v_max_i32_e32 v0, 0, v16
	v_lshlrev_b64 v[2:3], s22, v[0:1]
	v_or_b32_e32 v0, 1, v0
	v_lshlrev_b64 v[6:7], s22, v[0:1]
	v_lshl_add_u64 v[2:3], v[2:3], 0, s[18:19]
	v_lshl_add_u64 v[6:7], v[6:7], 0, s[18:19]
	v_mad_u64_u32 v[4:5], s[2:3], v2, s89, v[10:11]
	v_mad_u64_u32 v[8:9], s[2:3], v6, s89, v[10:11]
	v_mad_u32_u24 v5, v3, s89, v5
	v_mad_u32_u24 v9, v7, s89, v9
	s_waitcnt vmcnt(10)
	v_mov_b64_e32 v[2:3], v[92:93]
	v_mov_b64_e32 v[4:5], v[94:95]
	v_cmp_gt_i32_e32 vcc, 0, v16
	v_mov_b64_e32 v[6:7], v[96:97]
	v_mov_b64_e32 v[8:9], v[98:99]
	v_lshlrev_b32_e32 v15, 1, v15
	v_and_b32_e32 v15, 12, v15
	v_cndmask_b32_e64 v2, v2, 0, vcc
	v_cndmask_b32_e64 v3, v3, 0, vcc
	v_cndmask_b32_e64 v0, v9, 0, vcc
	v_ashrrev_i32_e32 v9, 6, v14
	v_bitop3_b32 v9, v9, v50, 15 bitop3:0x78
	v_cndmask_b32_e64 v6, v6, 0, vcc
	v_lshl_add_u32 v9, v9, 4, 0
	v_cndmask_b32_e64 v7, v7, 0, vcc
	v_perm_b32 v16, v2, v6, s13
	v_add3_u32 v9, v9, v15, v13
	v_perm_b32 v2, v2, v6, s14
	v_cndmask_b32_e64 v8, v8, 0, vcc
	v_cndmask_b32_e64 v4, v4, 0, vcc
	ds_write2_b32 v9, v16, v2 offset1:140
	v_perm_b32 v2, v3, v7, s13
	v_perm_b32 v3, v3, v7, s14
	v_add_u32_e32 v6, 0x400, v9
	v_cndmask_b32_e64 v5, v5, 0, vcc
	ds_write2_b32 v6, v2, v3 offset0:24 offset1:164
	v_perm_b32 v2, v4, v8, s13
	v_perm_b32 v3, v4, v8, s14
	v_add_u32_e32 v4, 0x800, v9
	v_add_u32_e32 v15, 0x600, v50
	ds_write2_b32 v4, v2, v3 offset0:48 offset1:188
	v_perm_b32 v2, v5, v0, s13
	v_perm_b32 v0, v5, v0, s14
	v_add_u32_e32 v3, 0xc00, v9
	v_ashrrev_i32_e32 v16, 3, v15
	ds_write2_b32 v3, v2, v0 offset0:72 offset1:212
	v_and_b32_e32 v0, -2, v16
	v_add_u32_e32 v17, s12, v0
	v_max_i32_e32 v0, 0, v17
	v_lshlrev_b64 v[2:3], s22, v[0:1]
	v_or_b32_e32 v0, 1, v0
	v_lshlrev_b64 v[6:7], s22, v[0:1]
	v_lshl_add_u64 v[2:3], v[2:3], 0, s[18:19]
	v_lshl_add_u64 v[6:7], v[6:7], 0, s[18:19]
	v_mad_u64_u32 v[4:5], s[2:3], v2, s89, v[10:11]
	v_mad_u64_u32 v[8:9], s[2:3], v6, s89, v[10:11]
	v_mad_u32_u24 v5, v3, s89, v5
	v_mad_u32_u24 v9, v7, s89, v9
	s_waitcnt vmcnt(8)
; __device__ void swa_item(const Params& p, int item) {
;     ...
;     if (j0 < 0) { v0 = (bf16x8){0, 0, 0, 0, 0, 0, 0, 0}; v1 = v0; }
;     const int chs = ((kp >> 2) ^ c8) * 8 + ((2 * kp) & 7);
;     _Pragma("unroll") for (int e = 0; e < 8; ++e)
;       *(unsigned*)(Vt + (c8 * 8 + e) * 280 + chs) = (unsigned)(bfu)v0[e] | ((unsigned)(bfu)v1[e] << 16);
;   }
;   _Pragma("unroll") for (int i = 0; i < 8; ++i) {
;     int co = tid + 512 * i; int c8 = co & 15, kj = co >> 4;
;     int j = qb * 128 - 128 + kj; j = (j >= 0) ? j : 0;
;     *(bf16x8*)(Ks + kj * 136 + c8 * 8) = *(const bf16x8*)(buf + (rowb + (long)j * dil + r) * 4608 + kcol + c8 * 8);
;   }
;   for (int i = tid; i < 128 * 12; i += NTHR) { int dv = i / 12, k2 = i % 12; *(unsigned*)(Vt + dv * 280 + 256 + 2 * k2) = 0u; }
	v_mov_b64_e32 v[2:3], v[100:101]
	v_mov_b64_e32 v[4:5], v[102:103]
	v_cmp_gt_i32_e32 vcc, 0, v17
	v_mov_b64_e32 v[6:7], v[104:105]
	v_mov_b64_e32 v[8:9], v[106:107]
	v_lshlrev_b32_e32 v10, 1, v16
	v_and_b32_e32 v10, 12, v10
	v_readlane_b32 s2, v254, 10
	v_cndmask_b32_e64 v2, v2, 0, vcc
	v_cndmask_b32_e64 v3, v3, 0, vcc
	v_cndmask_b32_e64 v0, v9, 0, vcc
	v_ashrrev_i32_e32 v9, 6, v15
	v_bitop3_b32 v9, v9, v50, 15 bitop3:0x78
	v_cndmask_b32_e64 v6, v6, 0, vcc
	v_lshl_add_u32 v9, v9, 4, 0
	v_cndmask_b32_e64 v7, v7, 0, vcc
	v_perm_b32 v11, v2, v6, s13
	v_add3_u32 v9, v9, v10, v13
	v_perm_b32 v2, v2, v6, s14
	v_cndmask_b32_e64 v8, v8, 0, vcc
	v_cndmask_b32_e64 v4, v4, 0, vcc
	ds_write2_b32 v9, v11, v2 offset1:140
	v_perm_b32 v2, v3, v7, s13
	v_perm_b32 v3, v3, v7, s14
	v_add_u32_e32 v6, 0x400, v9
	v_cndmask_b32_e64 v5, v5, 0, vcc
	ds_write2_b32 v6, v2, v3 offset0:24 offset1:164
	v_perm_b32 v2, v4, v8, s13
	v_perm_b32 v3, v4, v8, s14
	v_add_u32_e32 v4, 0x800, v9
	ds_write2_b32 v4, v2, v3 offset0:48 offset1:188
	v_perm_b32 v2, v5, v0, s13
	v_perm_b32 v0, v5, v0, s14
	v_add_u32_e32 v3, 0xc00, v9
	v_ashrrev_i32_e32 v7, 4, v50
	ds_write2_b32 v3, v2, v0 offset0:72 offset1:212
	v_add_u32_e32 v2, s12, v7
	v_lshlrev_b32_e32 v0, 3, v50
	v_max_i32_e32 v2, 0, v2
	v_mov_b32_e32 v3, v1
	v_and_b32_e32 v0, 0x78, v0
	v_lshlrev_b64 v[2:3], s22, v[2:3]
	v_lshlrev_b32_e32 v0, 1, v0
	v_lshl_add_u64 v[2:3], v[2:3], 0, s[18:19]
	v_mov_b64_e32 v[8:9], s[52:53]
	v_add_u32_e32 v6, s2, v0
	v_mad_u64_u32 v[4:5], s[2:3], v2, s89, v[8:9]
	v_mad_u32_u24 v5, v3, s89, v5
	v_lshl_add_u64 v[2:3], v[4:5], 0, v[0:1]
	s_waitcnt vmcnt(7)
	v_mov_b64_e32 v[2:3], v[108:109]
	v_mov_b64_e32 v[4:5], v[110:111]
	s_movk_i32 s13, 0x110
	v_mad_u64_u32 v[10:11], s[2:3], v7, s13, v[6:7]
	v_ashrrev_i32_e32 v7, 4, v51
	ds_write_b128 v10, v[2:5]
	v_add_u32_e32 v2, s12, v7
	v_max_i32_e32 v2, 0, v2
	v_mov_b32_e32 v3, v1
	v_lshlrev_b64 v[2:3], s22, v[2:3]
	v_lshl_add_u64 v[2:3], v[2:3], 0, s[18:19]
	v_mad_u64_u32 v[4:5], s[2:3], v2, s89, v[8:9]
	v_mad_u32_u24 v5, v3, s89, v5
	v_lshl_add_u64 v[2:3], v[4:5], 0, v[0:1]
	s_waitcnt vmcnt(6)
	v_mov_b64_e32 v[2:3], v[112:113]
	v_mov_b64_e32 v[4:5], v[114:115]
	v_mad_u64_u32 v[10:11], s[2:3], v7, s13, v[6:7]
	v_ashrrev_i32_e32 v7, 4, v14
	ds_write_b128 v10, v[2:5]
	v_add_u32_e32 v2, s12, v7
	v_max_i32_e32 v2, 0, v2
	v_mov_b32_e32 v3, v1
	v_lshlrev_b64 v[2:3], s22, v[2:3]
	v_lshl_add_u64 v[2:3], v[2:3], 0, s[18:19]
	v_mad_u64_u32 v[4:5], s[2:3], v2, s89, v[8:9]
	v_mad_u32_u24 v5, v3, s89, v5
	v_lshl_add_u64 v[2:3], v[4:5], 0, v[0:1]
	s_waitcnt vmcnt(5)
	v_mov_b64_e32 v[2:3], v[116:117]
	v_mov_b64_e32 v[4:5], v[118:119]
	v_mad_u64_u32 v[10:11], s[2:3], v7, s13, v[6:7]
	v_ashrrev_i32_e32 v7, 4, v15
	ds_write_b128 v10, v[2:5]
	v_add_u32_e32 v2, s12, v7
	v_max_i32_e32 v2, 0, v2
	v_mov_b32_e32 v3, v1
	v_lshlrev_b64 v[2:3], s22, v[2:3]
	v_lshl_add_u64 v[2:3], v[2:3], 0, s[18:19]
	v_mad_u64_u32 v[4:5], s[2:3], v2, s89, v[8:9]
	v_mad_u32_u24 v5, v3, s89, v5
	v_lshl_add_u64 v[2:3], v[4:5], 0, v[0:1]
	s_waitcnt vmcnt(4)
	v_mov_b64_e32 v[2:3], v[120:121]
	v_mov_b64_e32 v[4:5], v[122:123]
	v_mad_u64_u32 v[10:11], s[2:3], v7, s13, v[6:7]
	ds_write_b128 v10, v[2:5]
	v_add_u32_e32 v2, 0x800, v50
	v_ashrrev_i32_e32 v7, 4, v2
	v_add_u32_e32 v2, s12, v7
	v_max_i32_e32 v2, 0, v2
	v_mov_b32_e32 v3, v1
	v_lshlrev_b64 v[2:3], s22, v[2:3]
	v_lshl_add_u64 v[2:3], v[2:3], 0, s[18:19]
	v_mad_u64_u32 v[4:5], s[2:3], v2, s89, v[8:9]
	v_mad_u32_u24 v5, v3, s89, v5
	v_lshl_add_u64 v[2:3], v[4:5], 0, v[0:1]
	s_waitcnt vmcnt(3)
	v_mov_b64_e32 v[2:3], v[124:125]
	v_mov_b64_e32 v[4:5], v[126:127]
	v_mad_u64_u32 v[10:11], s[2:3], v7, s13, v[6:7]
	ds_write_b128 v10, v[2:5]
	v_add_u32_e32 v2, 0xa00, v50
	v_ashrrev_i32_e32 v7, 4, v2
	v_add_u32_e32 v2, s12, v7
	v_max_i32_e32 v2, 0, v2
	v_mov_b32_e32 v3, v1
	v_lshlrev_b64 v[2:3], s22, v[2:3]
	v_lshl_add_u64 v[2:3], v[2:3], 0, s[18:19]
	v_mad_u64_u32 v[4:5], s[2:3], v2, s89, v[8:9]
	v_mad_u32_u24 v5, v3, s89, v5
	v_lshl_add_u64 v[2:3], v[4:5], 0, v[0:1]
	s_waitcnt vmcnt(2)
	v_mov_b64_e32 v[2:3], v[128:129]
	v_mov_b64_e32 v[4:5], v[130:131]
	v_mad_u64_u32 v[10:11], s[2:3], v7, s13, v[6:7]
	ds_write_b128 v10, v[2:5]
	v_add_u32_e32 v2, 0xc00, v50
	v_ashrrev_i32_e32 v7, 4, v2
	v_add_u32_e32 v2, s12, v7
	v_max_i32_e32 v2, 0, v2
	v_mov_b32_e32 v3, v1
	v_lshlrev_b64 v[2:3], s22, v[2:3]
	v_lshl_add_u64 v[2:3], v[2:3], 0, s[18:19]
	v_mad_u64_u32 v[4:5], s[2:3], v2, s89, v[8:9]
	v_mad_u32_u24 v5, v3, s89, v5
	v_lshl_add_u64 v[2:3], v[4:5], 0, v[0:1]
	s_waitcnt vmcnt(1)
	v_mov_b64_e32 v[2:3], v[132:133]
	v_mov_b64_e32 v[4:5], v[134:135]
	v_mad_u64_u32 v[10:11], s[2:3], v7, s13, v[6:7]
	v_writelane_b32 v254, s18, 13
	ds_write_b128 v10, v[2:5]
	v_add_u32_e32 v2, 0xe00, v50
	v_ashrrev_i32_e32 v7, 4, v2
	v_add_u32_e32 v2, s12, v7
	v_max_i32_e32 v2, 0, v2
	v_mov_b32_e32 v3, v1
	v_lshlrev_b64 v[2:3], s22, v[2:3]
	v_lshl_add_u64 v[2:3], v[2:3], 0, s[18:19]
	v_mad_u64_u32 v[4:5], s[2:3], v2, s89, v[8:9]
	v_mad_u32_u24 v5, v3, s89, v5
	v_lshl_add_u64 v[2:3], v[4:5], 0, v[0:1]
	s_waitcnt vmcnt(0)
	v_mov_b64_e32 v[2:3], v[136:137]
	v_mov_b64_e32 v[4:5], v[138:139]
	v_mad_u64_u32 v[6:7], s[2:3], v7, s13, v[6:7]
	s_movk_i32 s2, 0x600
	v_writelane_b32 v254, s19, 14
	v_cmp_gt_i32_e32 vcc, s2, v50
	ds_write_b128 v6, v[2:5]
	s_and_saveexec_b64 s[12:13], vcc
	s_cbranch_execz .LBB0_111
	v_max_i32_e32 v2, 0x400, v50
	v_sub_u32_e32 v2, v2, v50
	v_add_u32_e32 v3, 0x1ff, v2
	v_cmp_lt_u32_e32 vcc, s24, v3
	s_mov_b64 s[18:19], -1
	v_mov_b32_e32 v2, v50
	s_and_saveexec_b64 s[14:15], vcc
	s_cbranch_execz .LBB0_108
	v_lshrrev_b32_e32 v2, 9, v3
	v_add_u32_e32 v4, 1, v2
	v_and_b32_e32 v5, 0xfffffe, v4
	s_mov_b64 s[18:19], 0
	v_mov_b32_e32 v6, v5
	v_mov_b64_e32 v[2:3], v[50:51]
	s_mov_b32 s2, 0x2aaaaaab
	s_movk_i32 s3, 0x230

; __device__ void swa_item(const Params& p, int item) {
;     ...
;   _Pragma("unroll") for (int i = 0; i < 4; ++i) {
;     int co = tid + 512 * i; int c8 = co & 15, kp = co >> 4;
;     int j0 = qb * 128 - 128 + 2 * kp;
;     const int j0c = (j0 >= 0) ? j0 : 0;
;     bf16x8 v0 = *(const bf16x8*)(buf + (rowb + (long)j0c * dil + r) * 4608 + vcol + c8 * 8);
;     bf16x8 v1 = *(const bf16x8*)(buf + (rowb + (long)(j0c + 1) * dil + r) * 4608 + vcol + c8 * 8);
;     if (j0 < 0) { v0 = (bf16x8){0, 0, 0, 0, 0, 0, 0, 0}; v1 = v0; }
;     const int chs = ((kp >> 2) ^ c8) * 8 + ((2 * kp) & 7);
;     _Pragma("unroll") for (int e = 0; e < 8; ++e)
;       *(unsigned*)(Vt + (c8 * 8 + e) * 280 + chs) = (unsigned)(bfu)v0[e] | ((unsigned)(bfu)v1[e] << 16);
;   }
;   _Pragma("unroll") for (int i = 0; i < 8; ++i) {
;     int co = tid + 512 * i; int c8 = co & 15, kj = co >> 4;
;     int j = qb * 128 - 128 + kj; j = (j >= 0) ? j : 0;
;     *(bf16x8*)(Ks + kj * 136 + c8 * 8) = *(const bf16x8*)(buf + (rowb + (long)j * dil + r) * 4608 + kcol + c8 * 8);
;     ...
;   bf16x8 qf[4];
;   { long qrow = rowb + (long)(qb * 128 + w * 16 + c) * dil + r;
;     _Pragma("unroll") for (int kk = 0; kk < 4; ++kk) qf[kk] = *(const bf16x8*)(buf + qrow * 4608 + qcol + kk * 32 + q * 8); }
;   __syncthreads();
;   f32x4 S[9];
;   _Pragma("unroll") for (int ci = 0; ci < 9; ++ci) {
;     const int ct = w + ci;
;     f32x4 a = (f32x4){0.f, 0.f, 0.f, 0.f};
;     _Pragma("unroll") for (int kk = 0; kk < 4; ++kk) {
;       bf16x8 kf = *(const bf16x8*)(Ks + (ct * 16 + c) * 136 + kk * 32 + q * 8);
;       a = __builtin_amdgcn_mfma_f32_16x16x32_bf16(qf[kk], kf, a, 0, 0, 0);
;     }
;     S[ci] = a;
;   }
.LBB0_111:
	s_or_b64 exec, exec, s[12:13]
	s_movk_i32 s2, 0x1500
	v_lshlrev_b32_e32 v58, 4, v12
	v_mul_lo_u32 v2, v12, s2
	v_readlane_b32 s12, v254, 10
	v_add_u32_e32 v51, s35, v58
	v_readlane_b32 s26, v254, 13
	v_add_u32_e32 v57, s12, v2
	v_or_b32_e32 v2, v51, v55
	v_ashrrev_i32_e32 v3, 31, v2
	v_lshlrev_b64 v[2:3], s22, v[2:3]
	v_readlane_b32 s27, v254, 14
	v_mov_b64_e32 v[4:5], s[16:17]
	v_and_b32_e32 v52, 48, v50
	v_lshl_add_u64 v[2:3], v[2:3], 0, s[26:27]
	v_mad_u64_u32 v[4:5], s[2:3], v2, s89, v[4:5]
	v_mad_i32_i24 v5, v3, s89, v5
	v_lshl_add_u64 v[2:3], s[0:1], 1, v[4:5]
	v_mov_b32_e32 v53, v1
	v_lshl_add_u64 v[2:3], v[2:3], 0, v[52:53]
	global_load_dwordx4 v[46:49], v[2:3], off
	global_load_dwordx4 v[42:45], v[2:3], off offset:64
	global_load_dwordx4 v[38:41], v[2:3], off offset:128
	global_load_dwordx4 v[34:37], v[2:3], off offset:192
	v_add_u32_e32 v54, s12, v52
	v_or_b32_e32 v53, v58, v55
	s_movk_i32 s3, 0x110
	v_mad_u64_u32 v[30:31], s[0:1], v53, s3, v[54:55]
	s_waitcnt lgkmcnt(0)
	s_barrier
	ds_read_b128 v[2:5], v30
	ds_read_b128 v[6:9], v30 offset:64
	v_bfe_u32 v56, v50, 4, 2
	s_cmp_lg_u32 s34, 0
	s_movk_i32 s2, 0x7f
	v_add_u32_e32 v62, 32, v53
	s_cselect_b64 s[14:15], -1, 0
	s_movk_i32 s18, 0x81
	v_add_u32_e32 v63, 48, v53
	v_add_u32_e32 v61, 16, v53
	v_add_u32_e32 v64, 64, v53
	v_add_u32_e32 v65, 0x50, v53
	v_add_u32_e32 v74, 0x60, v53
	v_add_u32_e32 v75, 0x70, v53
	v_and_b32_e32 v60, 63, v50
	s_waitcnt vmcnt(3) lgkmcnt(1)
	v_mfma_f32_16x16x32_bf16 v[2:5], v[46:49], v[2:5], 0
	ds_read_b128 v[10:13], v30 offset:4416
	ds_read_b128 v[14:17], v30 offset:8768
	ds_read_b128 v[18:21], v30 offset:13120
	s_waitcnt vmcnt(2) lgkmcnt(3)
	v_mfma_f32_16x16x32_bf16 v[2:5], v[42:45], v[6:9], v[2:5]
	ds_read_b128 v[6:9], v30 offset:128
	ds_read_b128 v[22:25], v30 offset:17472
	ds_read_b128 v[26:29], v30 offset:21824
	s_waitcnt vmcnt(1) lgkmcnt(2)
	v_mfma_f32_16x16x32_bf16 v[2:5], v[38:41], v[6:9], v[2:5]
	ds_read_b128 v[6:9], v30 offset:192
	ds_read_b128 v[66:69], v30 offset:26176
	ds_read_b128 v[70:73], v30 offset:30528
	s_waitcnt vmcnt(0) lgkmcnt(2)
	v_mfma_f32_16x16x32_bf16 v[2:5], v[34:37], v[6:9], v[2:5]
	v_mov_b32_e32 v150, s21
	v_mov_b32_e32 v151, s21
	v_add_u32_e32 v150, s30, v150
	v_cmp_gt_u32_e32 vcc, 0xc00, v150
	s_nop 1
	v_cndmask_b32_e32 v150, v151, v150, vcc
	v_lshrrev_b32_e32 v151, 10, v150
	v_lshlrev_b32_e32 v152, 1, v151
	v_and_b32_e32 v153, 31, v150
	v_mov_b32_e32 v154, 32
	v_lshrrev_b32_e32 v154, v152, v154
	v_add_u32_e32 v154, -1, v154
	v_and_b32_e32 v155, v154, v153
	v_sub_u32_e32 v156, 5, v152
	v_lshrrev_b32_e32 v156, v156, v153
	v_lshlrev_b32_e32 v157, 5, v150
	v_and_b32_e32 v157, 0x7000, v157
	v_or_b32_e32 v156, v156, v157
	v_lshlrev_b32_e32 v155, 7, v155
	v_add_u32_e32 v155, 0xffffff80, v155
	v_bfe_u32 v157, v150, 5, 2
	v_lshlrev_b32_e32 v157, 7, v157
	v_lshl_or_b32 v157, v151, 9, v157
	v_lshlrev_b32_e32 v157, 1, v157
	v_mbcnt_lo_u32_b32 v158, -1, 0
	v_mbcnt_hi_u32_b32 v158, -1, v158
	v_or_b32_e32 v158, s33, v158
	v_and_b32_e32 v140, 15, v158
	v_lshl_add_u32 v140, v140, 4, v157
	v_mov_b32_e32 v141, 0
	v_lshl_add_u64 v[140:141], s[16:17], 0, v[140:141]
	v_mov_b32_e32 v160, 0x1800
	v_mov_b32_e32 v161, 0
	v_lshl_add_u64 v[142:143], v[140:141], 0, v[160:161]
	v_mov_b32_e32 v159, 0x2400
	v_lshrrev_b32_e32 v144, 4, v158
	v_lshl_add_u32 v145, v144, 1, v155
	v_max_i32_e32 v146, 0, v145
	v_lshlrev_b32_e32 v147, v152, v146
	v_add_u32_e32 v147, v156, v147
	v_mad_u64_u32 v[148:149], vcc, v147, v159, v[142:143]
	global_load_dwordx4 v[76:79], v[148:149], off
	v_or_b32_e32 v146, 1, v146
	v_lshlrev_b32_e32 v147, v152, v146
	v_add_u32_e32 v147, v156, v147
	v_mad_u64_u32 v[148:149], vcc, v147, v159, v[142:143]
	global_load_dwordx4 v[80:83], v[148:149], off
	v_add_u32_e32 v146, 64, v145
	v_max_i32_e32 v146, 0, v146
	v_lshlrev_b32_e32 v147, v152, v146
	v_add_u32_e32 v147, v156, v147
	v_mad_u64_u32 v[148:149], vcc, v147, v159, v[142:143]
	global_load_dwordx4 v[84:87], v[148:149], off
	v_or_b32_e32 v146, 1, v146
	v_lshlrev_b32_e32 v147, v152, v146
	v_add_u32_e32 v147, v156, v147
	v_mad_u64_u32 v[148:149], vcc, v147, v159, v[142:143]
	global_load_dwordx4 v[88:91], v[148:149], off
	v_add_u32_e32 v146, 128, v145
	v_max_i32_e32 v146, 0, v146
	v_lshlrev_b32_e32 v147, v152, v146
	v_add_u32_e32 v147, v156, v147
	v_mad_u64_u32 v[148:149], vcc, v147, v159, v[142:143]
	global_load_dwordx4 v[92:95], v[148:149], off
	v_or_b32_e32 v146, 1, v146
	v_lshlrev_b32_e32 v147, v152, v146
	v_add_u32_e32 v147, v156, v147
	v_mad_u64_u32 v[148:149], vcc, v147, v159, v[142:143]
	global_load_dwordx4 v[96:99], v[148:149], off
	v_add_u32_e32 v146, 192, v145
	v_max_i32_e32 v146, 0, v146
	v_lshlrev_b32_e32 v147, v152, v146
	v_add_u32_e32 v147, v156, v147
	v_mad_u64_u32 v[148:149], vcc, v147, v159, v[142:143]
	global_load_dwordx4 v[100:103], v[148:149], off
	v_or_b32_e32 v146, 1, v146
	v_lshlrev_b32_e32 v147, v152, v146
	v_add_u32_e32 v147, v156, v147
	v_mad_u64_u32 v[148:149], vcc, v147, v159, v[142:143]
	global_load_dwordx4 v[104:107], v[148:149], off
	v_add_u32_e32 v145, v155, v144
	v_max_i32_e32 v146, 0, v145
	v_lshlrev_b32_e32 v147, v152, v146
	v_add_u32_e32 v147, v156, v147
	v_mad_u64_u32 v[148:149], vcc, v147, v159, v[140:141]
	global_load_dwordx4 v[108:111], v[148:149], off offset:3072
	v_add_u32_e32 v146, 32, v145
	v_max_i32_e32 v146, 0, v146
	v_lshlrev_b32_e32 v147, v152, v146
	v_add_u32_e32 v147, v156, v147
	v_mad_u64_u32 v[148:149], vcc, v147, v159, v[140:141]
	global_load_dwordx4 v[112:115], v[148:149], off offset:3072
	v_add_u32_e32 v146, 64, v145
	v_max_i32_e32 v146, 0, v146
	v_lshlrev_b32_e32 v147, v152, v146
	v_add_u32_e32 v147, v156, v147
	v_mad_u64_u32 v[148:149], vcc, v147, v159, v[140:141]
	global_load_dwordx4 v[116:119], v[148:149], off offset:3072
	v_add_u32_e32 v146, 96, v145
	v_max_i32_e32 v146, 0, v146
	v_lshlrev_b32_e32 v147, v152, v146
	v_add_u32_e32 v147, v156, v147
	v_mad_u64_u32 v[148:149], vcc, v147, v159, v[140:141]
	global_load_dwordx4 v[120:123], v[148:149], off offset:3072
	v_add_u32_e32 v146, 128, v145
	v_max_i32_e32 v146, 0, v146
	v_lshlrev_b32_e32 v147, v152, v146
	v_add_u32_e32 v147, v156, v147
	v_mad_u64_u32 v[148:149], vcc, v147, v159, v[140:141]
	global_load_dwordx4 v[124:127], v[148:149], off offset:3072
	v_add_u32_e32 v146, 160, v145
	v_max_i32_e32 v146, 0, v146
	v_lshlrev_b32_e32 v147, v152, v146
	v_add_u32_e32 v147, v156, v147
	v_mad_u64_u32 v[148:149], vcc, v147, v159, v[140:141]
	global_load_dwordx4 v[128:131], v[148:149], off offset:3072
	v_add_u32_e32 v146, 192, v145
	v_max_i32_e32 v146, 0, v146
	v_lshlrev_b32_e32 v147, v152, v146
	v_add_u32_e32 v147, v156, v147
	v_mad_u64_u32 v[148:149], vcc, v147, v159, v[140:141]
	global_load_dwordx4 v[132:135], v[148:149], off offset:3072
	v_add_u32_e32 v146, 224, v145
	v_max_i32_e32 v146, 0, v146
	v_lshlrev_b32_e32 v147, v152, v146
	v_add_u32_e32 v147, v156, v147
	v_mad_u64_u32 v[148:149], vcc, v147, v159, v[140:141]
	global_load_dwordx4 v[136:139], v[148:149], off offset:3072
	ds_read_b128 v[6:9], v30 offset:4352
	s_waitcnt lgkmcnt(0)
; #define SHX(v, m) shx_((v), (m), lane)
; __device__ void swa_item(const Params& p, int item) {
;     ...
;   _Pragma("unroll") for (int ci = 0; ci < 9; ++ci) {
;     const int ct = w + ci;
;     f32x4 a = (f32x4){0.f, 0.f, 0.f, 0.f};
;     _Pragma("unroll") for (int kk = 0; kk < 4; ++kk) {
;       bf16x8 kf = *(const bf16x8*)(Ks + (ct * 16 + c) * 136 + kk * 32 + q * 8);
;       a = __builtin_amdgcn_mfma_f32_16x16x32_bf16(qf[kk], kf, a, 0, 0, 0);
;     }
;     S[ci] = a;
;   }
;   float mx[4], ls[4];
;   _Pragma("unroll") for (int jj = 0; jj < 4; ++jj) {
;     const int qi = w * 16 + q * 4 + jj;
;     float m = -1e30f;
;     _Pragma("unroll") for (int ci = 0; ci < 9; ++ci) {
;       int kj = (w + ci) * 16 + c; int dist = qi + 128 - kj;
;       bool valid = (dist >= 0) && (dist <= 128) && (qb > 0 || kj >= 128);
;       float s = valid ? S[ci][jj] : -1e30f;
;       S[ci][jj] = s; m = fmaxf(m, s);
;     }
;     m = fmaxf(m, SHX(m, 1)); m = fmaxf(m, SHX(m, 2)); m = fmaxf(m, SHX(m, 4)); m = fmaxf(m, SHX(m, 8));
	v_mfma_f32_16x16x32_bf16 v[6:9], v[46:49], v[6:9], 0
	v_mfma_f32_16x16x32_bf16 v[6:9], v[42:45], v[10:13], v[6:9]
	ds_read_b128 v[10:13], v30 offset:4480
	s_waitcnt lgkmcnt(0)
	v_mfma_f32_16x16x32_bf16 v[6:9], v[38:41], v[10:13], v[6:9]
	ds_read_b128 v[10:13], v30 offset:4544
	s_waitcnt lgkmcnt(0)
	v_mfma_f32_16x16x32_bf16 v[6:9], v[34:37], v[10:13], v[6:9]
	ds_read_b128 v[10:13], v30 offset:8704
	s_waitcnt lgkmcnt(0)
	v_mfma_f32_16x16x32_bf16 v[10:13], v[46:49], v[10:13], 0
	v_mfma_f32_16x16x32_bf16 v[10:13], v[42:45], v[14:17], v[10:13]
	ds_read_b128 v[14:17], v30 offset:8832
	s_waitcnt lgkmcnt(0)
	v_mfma_f32_16x16x32_bf16 v[10:13], v[38:41], v[14:17], v[10:13]
	ds_read_b128 v[14:17], v30 offset:8896
	s_waitcnt lgkmcnt(0)
	v_mfma_f32_16x16x32_bf16 v[10:13], v[34:37], v[14:17], v[10:13]
	ds_read_b128 v[14:17], v30 offset:13056
	s_waitcnt lgkmcnt(0)
	v_mfma_f32_16x16x32_bf16 v[14:17], v[46:49], v[14:17], 0
	v_mfma_f32_16x16x32_bf16 v[14:17], v[42:45], v[18:21], v[14:17]
	ds_read_b128 v[18:21], v30 offset:13184
	s_waitcnt lgkmcnt(0)
	v_mfma_f32_16x16x32_bf16 v[14:17], v[38:41], v[18:21], v[14:17]
	ds_read_b128 v[18:21], v30 offset:13248
	s_waitcnt lgkmcnt(0)
	v_mfma_f32_16x16x32_bf16 v[14:17], v[34:37], v[18:21], v[14:17]
	ds_read_b128 v[18:21], v30 offset:17408
	s_waitcnt lgkmcnt(0)
	v_mfma_f32_16x16x32_bf16 v[18:21], v[46:49], v[18:21], 0
	v_mfma_f32_16x16x32_bf16 v[18:21], v[42:45], v[22:25], v[18:21]
	ds_read_b128 v[22:25], v30 offset:17536
	s_waitcnt lgkmcnt(0)
	v_mfma_f32_16x16x32_bf16 v[18:21], v[38:41], v[22:25], v[18:21]
	ds_read_b128 v[22:25], v30 offset:17600
	s_waitcnt lgkmcnt(0)
	v_mfma_f32_16x16x32_bf16 v[18:21], v[34:37], v[22:25], v[18:21]
	ds_read_b128 v[22:25], v30 offset:21760
	s_waitcnt lgkmcnt(0)
	v_mfma_f32_16x16x32_bf16 v[22:25], v[46:49], v[22:25], 0
	v_mfma_f32_16x16x32_bf16 v[22:25], v[42:45], v[26:29], v[22:25]
	ds_read_b128 v[26:29], v30 offset:21888
	s_waitcnt lgkmcnt(0)
	v_mfma_f32_16x16x32_bf16 v[22:25], v[38:41], v[26:29], v[22:25]
	ds_read_b128 v[26:29], v30 offset:21952
	s_waitcnt lgkmcnt(0)
	v_mfma_f32_16x16x32_bf16 v[22:25], v[34:37], v[26:29], v[22:25]
	ds_read_b128 v[26:29], v30 offset:26112
	s_waitcnt lgkmcnt(0)
	v_mfma_f32_16x16x32_bf16 v[26:29], v[46:49], v[26:29], 0
	v_mfma_f32_16x16x32_bf16 v[26:29], v[42:45], v[66:69], v[26:29]
	ds_read_b128 v[66:69], v30 offset:26240
	s_waitcnt lgkmcnt(0)
	v_mfma_f32_16x16x32_bf16 v[26:29], v[38:41], v[66:69], v[26:29]
	ds_read_b128 v[66:69], v30 offset:26304
	s_waitcnt lgkmcnt(0)
	v_mfma_f32_16x16x32_bf16 v[26:29], v[34:37], v[66:69], v[26:29]
	ds_read_b128 v[66:69], v30 offset:30464
	s_waitcnt lgkmcnt(0)
	v_mfma_f32_16x16x32_bf16 v[66:69], v[46:49], v[66:69], 0
	v_mfma_f32_16x16x32_bf16 v[66:69], v[42:45], v[70:73], v[66:69]
	ds_read_b128 v[70:73], v30 offset:30592
	ds_read_b128 v[30:33], v30 offset:30656
	s_waitcnt lgkmcnt(1)
	v_mfma_f32_16x16x32_bf16 v[66:69], v[38:41], v[70:73], v[66:69]
	v_add_u32_e32 v72, 0x80, v58
	v_or_b32_e32 v59, v72, v55
	v_mad_u64_u32 v[70:71], s[0:1], v59, s3, v[54:55]
	s_waitcnt lgkmcnt(0)
	v_mfma_f32_16x16x32_bf16 v[30:33], v[34:37], v[30:33], v[66:69]
	v_cmp_lt_i32_e64 s[0:1], s2, v53
	s_or_b64 s[12:13], s[14:15], s[0:1]
	v_cmp_lt_i32_e64 s[0:1], s2, v62
	ds_read_b128 v[66:69], v70
	s_waitcnt lgkmcnt(0)
	v_mfma_f32_16x16x32_bf16 v[46:49], v[46:49], v[66:69], 0
	ds_read_b128 v[66:69], v70 offset:64
	s_or_b64 s[38:39], s[14:15], s[0:1]
	v_cmp_lt_i32_e64 s[0:1], s2, v63
	s_waitcnt lgkmcnt(0)
	v_mfma_f32_16x16x32_bf16 v[42:45], v[42:45], v[66:69], v[46:49]
	v_mov_b32_e32 v66, 0xf149f2ca
	s_nop 1
	ds_read_b128 v[46:49], v70 offset:128
	s_or_b64 s[40:41], s[14:15], s[0:1]
	s_waitcnt lgkmcnt(0)
	v_mfma_f32_16x16x32_bf16 v[38:41], v[38:41], v[46:49], v[42:45]
	s_nop 2
	ds_read_b128 v[42:45], v70 offset:192
	v_cmp_lt_i32_e64 s[0:1], s2, v64
	s_or_b64 s[42:43], s[14:15], s[0:1]
	s_waitcnt lgkmcnt(0)
	v_mfma_f32_16x16x32_bf16 v[34:37], v[34:37], v[42:45], v[38:41]
	v_cmp_lt_i32_e64 s[0:1], s2, v65
	s_nop 1
	v_lshlrev_b32_e32 v38, 2, v56
	v_or_b32_e32 v43, v72, v38
	v_sub_u32_e32 v44, v43, v53
	v_cmp_gt_u32_e32 vcc, s18, v44
	s_and_b64 vcc, vcc, s[12:13]
	v_cndmask_b32_e64 v45, v66, v10, s[38:39]
	v_cndmask_b32_e32 v2, v66, v2, vcc
	v_cmp_lt_i32_e32 vcc, s2, v61
	v_max_f32_e32 v44, v2, v2
	s_or_b64 vcc, s[14:15], vcc
	v_max_f32_e32 v44, 0xf149f2ca, v44
	v_cndmask_b32_e32 v6, v66, v6, vcc
	s_or_b64 s[44:45], s[14:15], s[0:1]
	v_cmp_lt_i32_e64 s[0:1], s2, v74
	v_max3_f32 v10, v44, v6, v45
	v_cndmask_b32_e64 v44, v66, v18, s[42:43]
	s_or_b64 s[46:47], s[14:15], s[0:1]
	v_cmp_lt_i32_e64 s[0:1], s2, v75
	v_sub_u32_e32 v18, v38, v55
	v_cmp_lt_i32_e64 s[50:51], s2, v59
	v_cndmask_b32_e64 v14, v66, v14, s[40:41]
	s_or_b64 s[48:49], s[14:15], s[0:1]
	v_cmp_gt_u32_e64 s[0:1], s18, v18
	s_or_b64 s[14:15], s[14:15], s[50:51]
	v_max3_f32 v10, v10, v14, v44
	v_cndmask_b32_e64 v46, v66, v22, s[44:45]
	v_cndmask_b32_e64 v26, v66, v26, s[46:47]
	s_and_b64 s[0:1], s[0:1], s[14:15]
	v_lshlrev_b32_e32 v39, 2, v60
	v_max3_f32 v10, v10, v46, v26
	v_cndmask_b32_e64 v47, v66, v30, s[48:49]
	v_cndmask_b32_e64 v48, v66, v34, s[0:1]
	v_xor_b32_e32 v42, 4, v39
	v_max3_f32 v10, v10, v47, v48
	ds_bpermute_b32 v18, v42, v10
	v_xor_b32_e32 v41, 8, v39
	v_xor_b32_e32 v40, 16, v39
	v_xor_b32_e32 v39, 32, v39
	s_mov_b32 s2, 0xefa18f08
	s_waitcnt lgkmcnt(0)
	v_max_f32_e32 v18, v18, v18
	v_max_f32_e32 v10, v10, v18
	ds_bpermute_b32 v18, v41, v10
	v_cmp_lt_f32_e64 s[0:1], s2, v2
	v_cndmask_b32_e32 v7, v66, v7, vcc
	v_cndmask_b32_e64 v15, v66, v15, s[40:41]
	v_cndmask_b32_e64 v49, v66, v23, s[44:45]
	s_waitcnt lgkmcnt(0)
; __device__ __forceinline__ float fexp(float x) { return __builtin_amdgcn_exp2f(x * 1.4426950408889634f); }
; #define SHX(v, m) shx_((v), (m), lane)
; __device__ void swa_item(const Params& p, int item) {
;     ...
;   _Pragma("unroll") for (int jj = 0; jj < 4; ++jj) {
;     const int qi = w * 16 + q * 4 + jj;
;     float m = -1e30f;
;     _Pragma("unroll") for (int ci = 0; ci < 9; ++ci) {
;       int kj = (w + ci) * 16 + c; int dist = qi + 128 - kj;
;       bool valid = (dist >= 0) && (dist <= 128) && (qb > 0 || kj >= 128);
;       float s = valid ? S[ci][jj] : -1e30f;
;       S[ci][jj] = s; m = fmaxf(m, s);
;     }
;     m = fmaxf(m, SHX(m, 1)); m = fmaxf(m, SHX(m, 2)); m = fmaxf(m, SHX(m, 4)); m = fmaxf(m, SHX(m, 8));
;     float l = 0.f;
;     _Pragma("unroll") for (int ci = 0; ci < 9; ++ci) {
;       float s = S[ci][jj];
;       float pv = (s > -1e29f) ? fexp(s - m) : 0.f;
;       S[ci][jj] = pv; l += pv;
;     }
;     l += SHX(l, 1); l += SHX(l, 2); l += SHX(l, 4); l += SHX(l, 8);
;     mx[jj] = m; ls[jj] = l;
;   }
	v_max_f32_e32 v18, v18, v18
	v_max_f32_e32 v10, v10, v18
	ds_bpermute_b32 v18, v40, v10
	v_cndmask_b32_e64 v27, v66, v27, s[46:47]
	v_cndmask_b32_e64 v54, v66, v31, s[48:49]
	v_cndmask_b32_e32 v8, v66, v8, vcc
	v_cndmask_b32_e64 v12, v66, v12, s[38:39]
	s_waitcnt lgkmcnt(0)
	v_max_f32_e32 v18, v18, v18
	v_max_f32_e32 v10, v10, v18
	ds_bpermute_b32 v18, v39, v10
	v_cndmask_b32_e64 v60, v66, v32, s[48:49]
	v_cndmask_b32_e64 v16, v66, v16, s[40:41]
	v_cndmask_b32_e64 v20, v66, v20, s[42:43]
	v_cndmask_b32_e64 v28, v66, v28, s[46:47]
	s_waitcnt lgkmcnt(0)
	v_max_f32_e32 v18, v18, v18
	v_max_f32_e32 v22, v10, v18
	v_sub_f32_e32 v2, v2, v22
	v_mul_f32_e32 v2, 0x3fb8aa3b, v2
	v_exp_f32_e32 v2, v2
	v_sub_f32_e32 v34, v46, v22
	v_mul_f32_e32 v34, 0x3fb8aa3b, v34
	v_exp_f32_e32 v34, v34
	v_cndmask_b32_e64 v2, 0, v2, s[0:1]
	v_cmp_lt_f32_e64 s[0:1], s2, v6
	v_sub_f32_e32 v6, v6, v22
	v_mul_f32_e32 v6, 0x3fb8aa3b, v6
	v_exp_f32_e32 v6, v6
	v_add_f32_e32 v18, 0, v2
	v_cndmask_b32_e32 v9, v66, v9, vcc
	v_cndmask_b32_e64 v13, v66, v13, s[38:39]
	v_cndmask_b32_e64 v10, 0, v6, s[0:1]
	v_sub_f32_e32 v6, v45, v22
	v_mul_f32_e32 v6, 0x3fb8aa3b, v6
	v_exp_f32_e32 v6, v6
	v_cmp_lt_f32_e64 s[0:1], s2, v45
	v_add_f32_e32 v18, v10, v18
	v_cndmask_b32_e64 v17, v66, v17, s[40:41]
	v_cndmask_b32_e64 v6, 0, v6, s[0:1]
	v_cmp_lt_f32_e64 s[0:1], s2, v14
	v_sub_f32_e32 v14, v14, v22
	v_mul_f32_e32 v14, 0x3fb8aa3b, v14
	v_exp_f32_e32 v14, v14
	v_add_f32_e32 v30, v6, v18
	v_cndmask_b32_e64 v21, v66, v21, s[42:43]
	v_cndmask_b32_e64 v29, v66, v29, s[46:47]
	v_cndmask_b32_e64 v18, 0, v14, s[0:1]
	v_sub_f32_e32 v14, v44, v22
	v_mul_f32_e32 v14, 0x3fb8aa3b, v14
	v_exp_f32_e32 v14, v14
	v_cmp_lt_f32_e64 s[0:1], s2, v44
	v_add_f32_e32 v30, v18, v30
	v_cndmask_b32_e64 v33, v66, v33, s[48:49]
	v_cndmask_b32_e64 v14, 0, v14, s[0:1]
	v_cmp_lt_f32_e64 s[0:1], s2, v46
	v_add_f32_e32 v30, v14, v30
	s_nop 0
	v_cndmask_b32_e64 v34, 0, v34, s[0:1]
	v_cmp_lt_f32_e64 s[0:1], s2, v26
	v_sub_f32_e32 v26, v26, v22
	v_mul_f32_e32 v26, 0x3fb8aa3b, v26
	v_exp_f32_e32 v26, v26
	v_add_f32_e32 v44, v34, v30
	s_barrier
	global_load_dword v243, v240, s[52:53]
	global_load_dword v243, v241, s[52:53]
	global_load_dword v243, v242, s[52:53]
	v_cndmask_b32_e64 v30, 0, v26, s[0:1]
	v_add_f32_e32 v26, v30, v44
	v_sub_f32_e32 v44, v47, v22
	v_mul_f32_e32 v44, 0x3fb8aa3b, v44
	v_exp_f32_e32 v44, v44
	v_cmp_lt_f32_e64 s[0:1], s2, v47
	s_nop 1
	v_cndmask_b32_e64 v45, 0, v44, s[0:1]
	v_sub_f32_e32 v44, v48, v22
	v_mul_f32_e32 v44, 0x3fb8aa3b, v44
	v_exp_f32_e32 v44, v44
	v_cmp_lt_f32_e64 s[0:1], s2, v48
	v_add_f32_e32 v26, v45, v26
	v_cndmask_b32_e64 v48, v66, v11, s[38:39]
	v_cndmask_b32_e64 v44, 0, v44, s[0:1]
	v_add_f32_e32 v26, v44, v26
	ds_bpermute_b32 v46, v42, v26
	s_waitcnt lgkmcnt(0)
	v_add_f32_e32 v26, v26, v46
	ds_bpermute_b32 v46, v41, v26
	s_waitcnt lgkmcnt(0)
	v_add_f32_e32 v26, v26, v46
	ds_bpermute_b32 v46, v40, v26
	s_waitcnt lgkmcnt(0)
	v_add_f32_e32 v26, v26, v46
	ds_bpermute_b32 v46, v39, v26
	s_waitcnt lgkmcnt(0)
	v_add_f32_e32 v26, v26, v46
	v_or_b32_e32 v46, 1, v43
	v_sub_u32_e32 v47, v46, v53
	v_cmp_gt_u32_e64 s[0:1], s18, v47
	s_and_b64 s[0:1], s[0:1], s[12:13]
	s_nop 0
	v_cndmask_b32_e64 v3, v66, v3, s[0:1]
	v_max_f32_e32 v47, v3, v3
	v_max_f32_e32 v47, 0xf149f2ca, v47
	v_max3_f32 v11, v47, v7, v48
	v_cndmask_b32_e64 v47, v66, v19, s[42:43]
	v_sub_u32_e32 v19, v46, v59
	v_cmp_gt_u32_e64 s[0:1], s18, v19
	v_max3_f32 v11, v11, v15, v47
	s_and_b64 s[0:1], s[0:1], s[14:15]
	v_max3_f32 v11, v11, v49, v27
	v_cndmask_b32_e64 v35, v66, v35, s[0:1]
	v_max3_f32 v11, v11, v54, v35
	ds_bpermute_b32 v19, v42, v11
	v_cmp_lt_f32_e64 s[0:1], s2, v3
	s_waitcnt lgkmcnt(0)
	v_max_f32_e32 v19, v19, v19
	v_max_f32_e32 v11, v11, v19
	ds_bpermute_b32 v19, v41, v11
	s_waitcnt lgkmcnt(0)
	v_max_f32_e32 v19, v19, v19
	v_max_f32_e32 v11, v11, v19
	ds_bpermute_b32 v19, v40, v11
	s_waitcnt lgkmcnt(0)
	v_max_f32_e32 v19, v19, v19
	v_max_f32_e32 v11, v11, v19
	ds_bpermute_b32 v19, v39, v11
	s_waitcnt lgkmcnt(0)
	v_max_f32_e32 v19, v19, v19
	v_max_f32_e32 v23, v11, v19
	v_sub_f32_e32 v3, v3, v23
	v_mul_f32_e32 v3, 0x3fb8aa3b, v3
	v_exp_f32_e32 v3, v3
	v_sub_f32_e32 v46, v49, v23
	v_mul_f32_e32 v46, 0x3fb8aa3b, v46
	v_exp_f32_e32 v46, v46
	v_cndmask_b32_e64 v3, 0, v3, s[0:1]
	v_cmp_lt_f32_e64 s[0:1], s2, v7
	v_sub_f32_e32 v7, v7, v23
	v_mul_f32_e32 v7, 0x3fb8aa3b, v7
	v_exp_f32_e32 v7, v7
	v_add_f32_e32 v19, 0, v3
	v_cndmask_b32_e64 v11, 0, v7, s[0:1]
	v_sub_f32_e32 v7, v48, v23
	v_mul_f32_e32 v7, 0x3fb8aa3b, v7
	v_exp_f32_e32 v7, v7
	v_cmp_lt_f32_e64 s[0:1], s2, v48
	v_add_f32_e32 v19, v11, v19
	s_nop 0
	v_cndmask_b32_e64 v7, 0, v7, s[0:1]
	v_cmp_lt_f32_e64 s[0:1], s2, v15
	v_sub_f32_e32 v15, v15, v23
	v_mul_f32_e32 v15, 0x3fb8aa3b, v15
	v_exp_f32_e32 v15, v15
	v_add_f32_e32 v31, v7, v19
	v_cndmask_b32_e64 v19, 0, v15, s[0:1]
	v_sub_f32_e32 v15, v47, v23
	v_mul_f32_e32 v15, 0x3fb8aa3b, v15
	v_exp_f32_e32 v15, v15
	v_cmp_lt_f32_e64 s[0:1], s2, v47
	v_add_f32_e32 v31, v19, v31
	s_nop 0
	v_cndmask_b32_e64 v15, 0, v15, s[0:1]
	v_cmp_lt_f32_e64 s[0:1], s2, v49
	v_add_f32_e32 v31, v15, v31
	s_nop 0
	v_cndmask_b32_e64 v46, 0, v46, s[0:1]
	v_cmp_lt_f32_e64 s[0:1], s2, v27
	v_sub_f32_e32 v27, v27, v23
	v_mul_f32_e32 v27, 0x3fb8aa3b, v27
	v_exp_f32_e32 v27, v27
	v_add_f32_e32 v47, v46, v31
	v_cndmask_b32_e64 v31, 0, v27, s[0:1]
	v_add_f32_e32 v27, v31, v47
	v_sub_f32_e32 v47, v54, v23
	v_mul_f32_e32 v47, 0x3fb8aa3b, v47
	v_exp_f32_e32 v47, v47
	v_cmp_lt_f32_e64 s[0:1], s2, v54
	v_cndmask_b32_e64 v54, v66, v24, s[44:45]
	s_nop 0
	v_cndmask_b32_e64 v47, 0, v47, s[0:1]
	v_cmp_lt_f32_e64 s[0:1], s2, v35
	v_sub_f32_e32 v35, v35, v23
	v_mul_f32_e32 v35, 0x3fb8aa3b, v35
	v_exp_f32_e32 v35, v35
	v_add_f32_e32 v27, v47, v27
	v_cndmask_b32_e64 v35, 0, v35, s[0:1]
	v_add_f32_e32 v27, v35, v27
	ds_bpermute_b32 v48, v42, v27
	s_waitcnt lgkmcnt(0)
; __device__ __forceinline__ float fexp(float x) { return __builtin_amdgcn_exp2f(x * 1.4426950408889634f); }
; #define SHX(v, m) shx_((v), (m), lane)
; __device__ void swa_item(const Params& p, int item) {
;     ...
;   _Pragma("unroll") for (int jj = 0; jj < 4; ++jj) {
;     const int qi = w * 16 + q * 4 + jj;
;     float m = -1e30f;
;     _Pragma("unroll") for (int ci = 0; ci < 9; ++ci) {
;       int kj = (w + ci) * 16 + c; int dist = qi + 128 - kj;
;       bool valid = (dist >= 0) && (dist <= 128) && (qb > 0 || kj >= 128);
;       float s = valid ? S[ci][jj] : -1e30f;
;       S[ci][jj] = s; m = fmaxf(m, s);
;     }
;     m = fmaxf(m, SHX(m, 1)); m = fmaxf(m, SHX(m, 2)); m = fmaxf(m, SHX(m, 4)); m = fmaxf(m, SHX(m, 8));
;     float l = 0.f;
;     _Pragma("unroll") for (int ci = 0; ci < 9; ++ci) {
;       float s = S[ci][jj];
;       float pv = (s > -1e29f) ? fexp(s - m) : 0.f;
;       S[ci][jj] = pv; l += pv;
;     }
;     l += SHX(l, 1); l += SHX(l, 2); l += SHX(l, 4); l += SHX(l, 8);
;     mx[jj] = m; ls[jj] = l;
;   }
	v_add_f32_e32 v27, v27, v48
	ds_bpermute_b32 v48, v41, v27
	s_waitcnt lgkmcnt(0)
	v_add_f32_e32 v27, v27, v48
	ds_bpermute_b32 v48, v40, v27
	s_waitcnt lgkmcnt(0)
	v_add_f32_e32 v27, v27, v48
	ds_bpermute_b32 v48, v39, v27
	s_waitcnt lgkmcnt(0)
	v_add_f32_e32 v27, v27, v48
	v_or_b32_e32 v48, 2, v43
	v_sub_u32_e32 v49, v48, v53
	v_cmp_gt_u32_e64 s[0:1], s18, v49
	s_and_b64 s[0:1], s[0:1], s[12:13]
	v_sub_u32_e32 v32, v48, v59
	v_cndmask_b32_e64 v4, v66, v4, s[0:1]
	v_max_f32_e32 v49, v4, v4
	v_max_f32_e32 v49, 0xf149f2ca, v49
	v_max3_f32 v49, v49, v8, v12
	v_cmp_gt_u32_e64 s[0:1], s18, v32
	v_max3_f32 v49, v49, v16, v20
	s_and_b64 s[0:1], s[0:1], s[14:15]
	v_max3_f32 v24, v49, v54, v28
	v_cndmask_b32_e64 v61, v66, v36, s[0:1]
	v_max3_f32 v24, v24, v60, v61
	ds_bpermute_b32 v32, v42, v24
	v_cmp_lt_f32_e64 s[0:1], s2, v4
	v_or_b32_e32 v43, 3, v43
	v_sub_u32_e32 v53, v43, v53
	v_sub_u32_e32 v43, v43, v59
	s_waitcnt lgkmcnt(0)
	v_max_f32_e32 v32, v32, v32
	v_max_f32_e32 v24, v24, v32
	ds_bpermute_b32 v32, v41, v24
	v_cmp_gt_u32_e32 vcc, s18, v43
	s_and_b64 vcc, vcc, s[14:15]
	s_waitcnt lgkmcnt(0)
	v_max_f32_e32 v32, v32, v32
	v_max_f32_e32 v24, v24, v32
	ds_bpermute_b32 v32, v40, v24
	v_cndmask_b32_e32 v37, v66, v37, vcc
	s_waitcnt lgkmcnt(0)
	v_max_f32_e32 v32, v32, v32
	v_max_f32_e32 v24, v24, v32
	ds_bpermute_b32 v32, v39, v24
	s_waitcnt lgkmcnt(0)
	v_max_f32_e32 v32, v32, v32
	v_max_f32_e32 v24, v24, v32
	v_sub_f32_e32 v4, v4, v24
	v_mul_f32_e32 v4, 0x3fb8aa3b, v4
	v_exp_f32_e32 v4, v4
	s_nop 0
	v_cndmask_b32_e64 v4, 0, v4, s[0:1]
	v_cmp_lt_f32_e64 s[0:1], s2, v8
	v_sub_f32_e32 v8, v8, v24
	v_mul_f32_e32 v8, 0x3fb8aa3b, v8
	v_exp_f32_e32 v8, v8
	v_add_f32_e32 v32, 0, v4
	v_cndmask_b32_e64 v8, 0, v8, s[0:1]
	v_cmp_lt_f32_e64 s[0:1], s2, v12
	v_sub_f32_e32 v12, v12, v24
	v_mul_f32_e32 v12, 0x3fb8aa3b, v12
	v_exp_f32_e32 v12, v12
	v_add_f32_e32 v32, v8, v32
	v_cndmask_b32_e64 v12, 0, v12, s[0:1]
	v_cmp_lt_f32_e64 s[0:1], s2, v16
	v_sub_f32_e32 v16, v16, v24
	v_mul_f32_e32 v16, 0x3fb8aa3b, v16
	v_exp_f32_e32 v16, v16
	v_add_f32_e32 v32, v12, v32
	v_cndmask_b32_e64 v16, 0, v16, s[0:1]
	v_cmp_lt_f32_e64 s[0:1], s2, v20
	v_sub_f32_e32 v20, v20, v24
	v_mul_f32_e32 v20, 0x3fb8aa3b, v20
	v_exp_f32_e32 v20, v20
	v_add_f32_e32 v36, v16, v32
	v_cndmask_b32_e64 v32, 0, v20, s[0:1]
	v_add_f32_e32 v20, v32, v36
	v_sub_f32_e32 v36, v54, v24
	v_mul_f32_e32 v36, 0x3fb8aa3b, v36
	v_exp_f32_e32 v36, v36
	v_cmp_lt_f32_e64 s[0:1], s2, v54
	s_nop 1
	v_cndmask_b32_e64 v49, 0, v36, s[0:1]
	v_cmp_lt_f32_e64 s[0:1], s2, v28
	v_sub_f32_e32 v28, v28, v24
	v_mul_f32_e32 v28, 0x3fb8aa3b, v28
	v_exp_f32_e32 v28, v28
	v_add_f32_e32 v20, v49, v20
	v_cndmask_b32_e64 v48, 0, v28, s[0:1]
	v_sub_f32_e32 v28, v60, v24
	v_mul_f32_e32 v28, 0x3fb8aa3b, v28
	v_exp_f32_e32 v28, v28
	v_cmp_lt_f32_e64 s[0:1], s2, v60
	v_add_f32_e32 v20, v48, v20
	s_nop 0
	v_cndmask_b32_e64 v36, 0, v28, s[0:1]
	v_add_f32_e32 v28, v36, v20
	v_sub_f32_e32 v20, v61, v24
	v_mul_f32_e32 v20, 0x3fb8aa3b, v20
	v_exp_f32_e32 v20, v20
	v_cmp_lt_f32_e64 s[0:1], s2, v61
	s_nop 1
	v_cndmask_b32_e64 v20, 0, v20, s[0:1]
	v_add_f32_e32 v28, v20, v28
	ds_bpermute_b32 v54, v42, v28
	v_cmp_gt_u32_e64 s[0:1], s18, v53
	s_and_b64 s[0:1], s[0:1], s[12:13]
	s_waitcnt lgkmcnt(0)
	v_add_f32_e32 v28, v28, v54
	ds_bpermute_b32 v54, v41, v28
	v_cndmask_b32_e64 v5, v66, v5, s[0:1]
	v_max_f32_e32 v53, v5, v5
	v_max_f32_e32 v53, 0xf149f2ca, v53
	v_max3_f32 v53, v53, v9, v13
	s_waitcnt lgkmcnt(0)
	v_add_f32_e32 v28, v28, v54
	ds_bpermute_b32 v54, v40, v28
	v_max3_f32 v53, v53, v17, v21
	v_cmp_lt_f32_e32 vcc, s2, v5
	s_movk_i32 s0, 0x540
	s_waitcnt lgkmcnt(0)
	v_add_f32_e32 v28, v28, v54
	ds_bpermute_b32 v54, v39, v28
	s_waitcnt lgkmcnt(0)
	v_add_f32_e32 v28, v28, v54
	v_cndmask_b32_e64 v54, v66, v25, s[44:45]
	v_max3_f32 v25, v53, v54, v29
	v_max3_f32 v25, v25, v33, v37
	ds_bpermute_b32 v43, v42, v25
	s_waitcnt lgkmcnt(0)
	v_max_f32_e32 v43, v43, v43
	v_max_f32_e32 v25, v25, v43
	ds_bpermute_b32 v43, v41, v25
	s_waitcnt lgkmcnt(0)
	v_max_f32_e32 v43, v43, v43
	v_max_f32_e32 v25, v25, v43
	ds_bpermute_b32 v43, v40, v25
	s_waitcnt lgkmcnt(0)
	v_max_f32_e32 v43, v43, v43
	v_max_f32_e32 v25, v25, v43
	ds_bpermute_b32 v43, v39, v25
	s_waitcnt lgkmcnt(0)
	v_max_f32_e32 v43, v43, v43
	v_max_f32_e32 v25, v25, v43
	v_sub_f32_e32 v5, v5, v25
	v_mul_f32_e32 v5, 0x3fb8aa3b, v5
	v_exp_f32_e32 v5, v5
	v_sub_f32_e32 v53, v54, v25
	v_mul_f32_e32 v53, 0x3fb8aa3b, v53
	v_exp_f32_e32 v53, v53
	v_cndmask_b32_e32 v5, 0, v5, vcc
	v_cmp_lt_f32_e32 vcc, s2, v9
	v_sub_f32_e32 v9, v9, v25
	v_mul_f32_e32 v9, 0x3fb8aa3b, v9
	v_exp_f32_e32 v9, v9
	v_add_f32_e32 v43, 0, v5
	v_cndmask_b32_e32 v9, 0, v9, vcc
	v_cmp_lt_f32_e32 vcc, s2, v13
	v_sub_f32_e32 v13, v13, v25
	v_mul_f32_e32 v13, 0x3fb8aa3b, v13
	v_exp_f32_e32 v13, v13
	v_add_f32_e32 v43, v9, v43
	v_cndmask_b32_e32 v13, 0, v13, vcc
	v_cmp_lt_f32_e32 vcc, s2, v17
	v_sub_f32_e32 v17, v17, v25
	v_mul_f32_e32 v17, 0x3fb8aa3b, v17
	v_exp_f32_e32 v17, v17
	v_add_f32_e32 v43, v13, v43
	v_cndmask_b32_e32 v17, 0, v17, vcc
	v_cmp_lt_f32_e32 vcc, s2, v21
	v_sub_f32_e32 v21, v21, v25
	v_mul_f32_e32 v21, 0x3fb8aa3b, v21
	v_exp_f32_e32 v21, v21
	v_add_f32_e32 v43, v17, v43
	v_cndmask_b32_e32 v21, 0, v21, vcc
	v_cmp_lt_f32_e32 vcc, s2, v54
	v_add_f32_e32 v43, v21, v43
	s_nop 0
	v_cndmask_b32_e32 v53, 0, v53, vcc
	v_cmp_lt_f32_e32 vcc, s2, v29
	v_sub_f32_e32 v29, v29, v25
	v_mul_f32_e32 v29, 0x3fb8aa3b, v29
	v_exp_f32_e32 v29, v29
	v_add_f32_e32 v43, v53, v43
	v_cndmask_b32_e32 v54, 0, v29, vcc
	v_cmp_lt_f32_e32 vcc, s2, v33
	v_sub_f32_e32 v33, v33, v25
	v_mul_f32_e32 v33, 0x3fb8aa3b, v33
	v_exp_f32_e32 v33, v33
	v_add_f32_e32 v29, v54, v43
	v_or_b32_e32 v43, 1, v38
	v_cndmask_b32_e32 v33, 0, v33, vcc
	v_cmp_lt_f32_e32 vcc, s2, v37
	v_sub_f32_e32 v37, v37, v25
	v_mul_f32_e32 v37, 0x3fb8aa3b, v37
	v_exp_f32_e32 v37, v37
	v_add_f32_e32 v29, v33, v29
	s_movk_i32 s2, 0xc0
	v_cndmask_b32_e32 v37, 0, v37, vcc
	v_add_f32_e32 v29, v37, v29
	ds_bpermute_b32 v42, v42, v29
	s_waitcnt lgkmcnt(0)
; __device__ __forceinline__ float frcp(float x) { return __builtin_amdgcn_rcpf(x); }
; #define SHX(v, m) shx_((v), (m), lane)
; __device__ void swa_item(const Params& p, int item) {
;     ...
;     l += SHX(l, 1); l += SHX(l, 2); l += SHX(l, 4); l += SHX(l, 8);
;     mx[jj] = m; ls[jj] = l;
;   }
;   __syncthreads();
;   _Pragma("unroll") for (int ci = 0; ci < 9; ++ci) _Pragma("unroll") for (int jj = 0; jj < 4; ++jj) Pl[(q * 4 + jj) * 168 + ci * 16 + c] = f2bf(S[ci][jj]);
;   _Pragma("unroll") for (int jj = 0; jj < 4; ++jj) Pl[(q * 4 + jj) * 168 + 144 + c] = 0;
;   asm volatile("s_waitcnt lgkmcnt(0)" ::: "memory");
;   bf16x8 pf[5];
;   _Pragma("unroll") for (int kk = 0; kk < 5; ++kk) pf[kk] = *(const bf16x8*)(Pl + c * 168 + kk * 32 + q * 8);
;   asm volatile("s_waitcnt lgkmcnt(0)" ::: "memory");
;   float il[4];
;   _Pragma("unroll") for (int jj = 0; jj < 4; ++jj) il[jj] = frcp(ls[jj]);
;   bfu* Ow = Pl;
;   _Pragma("unroll") for (int dt = 0; dt < 8; ++dt) {
;     f32x4 a = (f32x4){0.f, 0.f, 0.f, 0.f};
;     _Pragma("unroll") for (int kk = 0; kk < 5; ++kk) {
;       const int k0_ = w * 16 + kk * 32 + q * 8; const int ch_ = k0_ >> 3;
;       const int chp_ = (ch_ < 32) ? (ch_ ^ (((dt * 16 + c) >> 3) & 15)) : ch_;
;       bf16x8 vf = *(const bf16x8*)(Vt + (dt * 16 + c) * 280 + chp_ * 8);
;       a = __builtin_amdgcn_mfma_f32_16x16x32_bf16(pf[kk], vf, a, 0, 0, 0);
	v_add_f32_e32 v29, v29, v42
	ds_bpermute_b32 v41, v41, v29
	s_waitcnt lgkmcnt(0)
	v_add_f32_e32 v29, v29, v41
	ds_bpermute_b32 v40, v40, v29
	v_bfe_u32 v41, v2, 16, 1
	v_add3_u32 v2, v2, v41, s72
	v_mul_u32_u24_e32 v41, 0x540, v56
	s_waitcnt lgkmcnt(0)
	v_add_f32_e32 v29, v29, v40
	ds_bpermute_b32 v39, v39, v29
	s_waitcnt lgkmcnt(0)
	v_add_f32_e32 v29, v29, v39
	v_lshlrev_b32_e32 v39, 1, v55
	v_add_u32_e32 v40, v57, v39
	v_mad_u32_u24 v42, v56, s0, v40
	ds_write_b16_d16_hi v42, v2
	v_bfe_u32 v2, v3, 16, 1
	s_movk_i32 s0, 0x150
	v_add3_u32 v2, v3, v2, s72
	v_mad_u32_u24 v59, v43, s0, v40
	ds_write_b16_d16_hi v59, v2
	v_bfe_u32 v2, v4, 16, 1
	v_add3_u32 v2, v4, v2, s72
	v_mad_u32_u24 v4, v43, s0, s0
	v_add_u32_e32 v60, v40, v4
	ds_write_b16_d16_hi v60, v2
	v_bfe_u32 v2, v5, 16, 1
	v_add3_u32 v2, v5, v2, s72
	v_mov_b32_e32 v5, 0x2a0
	v_mad_u32_u24 v5, v43, s0, v5
	v_add_u32_e32 v61, v40, v5
	ds_write_b16_d16_hi v61, v2
	v_bfe_u32 v2, v10, 16, 1
	v_add3_u32 v2, v10, v2, s72
	ds_write_b16_d16_hi v42, v2 offset:32
	v_bfe_u32 v2, v11, 16, 1
	v_add3_u32 v2, v11, v2, s72
	ds_write_b16_d16_hi v59, v2 offset:32
	v_bfe_u32 v2, v8, 16, 1
	v_add3_u32 v2, v8, v2, s72
	ds_write_b16_d16_hi v60, v2 offset:32
	v_bfe_u32 v2, v9, 16, 1
	v_add3_u32 v2, v9, v2, s72
	ds_write_b16_d16_hi v61, v2 offset:32
	v_bfe_u32 v2, v6, 16, 1
	v_add3_u32 v2, v6, v2, s72
	ds_write_b16_d16_hi v42, v2 offset:64
	v_bfe_u32 v2, v7, 16, 1
	v_add3_u32 v2, v7, v2, s72
	ds_write_b16_d16_hi v59, v2 offset:64
	v_bfe_u32 v2, v12, 16, 1
	v_add3_u32 v2, v12, v2, s72
	ds_write_b16_d16_hi v60, v2 offset:64
	v_bfe_u32 v2, v13, 16, 1
	v_add3_u32 v2, v13, v2, s72
	ds_write_b16_d16_hi v61, v2 offset:64
	v_bfe_u32 v2, v18, 16, 1
	v_add3_u32 v2, v18, v2, s72
	ds_write_b16_d16_hi v42, v2 offset:96
	v_bfe_u32 v2, v19, 16, 1
	v_add3_u32 v2, v19, v2, s72
	ds_write_b16_d16_hi v59, v2 offset:96
	v_bfe_u32 v2, v16, 16, 1
	v_add3_u32 v2, v16, v2, s72
	ds_write_b16_d16_hi v60, v2 offset:96
	v_bfe_u32 v2, v17, 16, 1
	v_add3_u32 v2, v17, v2, s72
	ds_write_b16_d16_hi v61, v2 offset:96
	v_bfe_u32 v2, v14, 16, 1
	v_add3_u32 v2, v14, v2, s72
	ds_write_b16_d16_hi v42, v2 offset:128
	v_bfe_u32 v2, v15, 16, 1
	v_add3_u32 v2, v15, v2, s72
	ds_write_b16_d16_hi v59, v2 offset:128
	v_bfe_u32 v2, v32, 16, 1
	v_add3_u32 v2, v32, v2, s72
	ds_write_b16_d16_hi v60, v2 offset:128
	v_bfe_u32 v2, v21, 16, 1
	v_add3_u32 v2, v21, v2, s72
	ds_write_b16_d16_hi v61, v2 offset:128
	v_bfe_u32 v2, v34, 16, 1
	v_add3_u32 v2, v34, v2, s72
	ds_write_b16_d16_hi v42, v2 offset:160
	v_bfe_u32 v2, v46, 16, 1
	v_add3_u32 v2, v46, v2, s72
	ds_write_b16_d16_hi v59, v2 offset:160
	v_bfe_u32 v2, v49, 16, 1
	v_add3_u32 v2, v49, v2, s72
	ds_write_b16_d16_hi v60, v2 offset:160
	v_bfe_u32 v2, v53, 16, 1
	v_add3_u32 v2, v53, v2, s72
	ds_write_b16_d16_hi v61, v2 offset:160
	v_bfe_u32 v2, v30, 16, 1
	v_add3_u32 v2, v30, v2, s72
	ds_write_b16_d16_hi v42, v2 offset:192
	v_bfe_u32 v2, v31, 16, 1
	v_add3_u32 v2, v31, v2, s72
	ds_write_b16_d16_hi v59, v2 offset:192
	v_bfe_u32 v2, v48, 16, 1
	v_add3_u32 v2, v48, v2, s72
	ds_write_b16_d16_hi v60, v2 offset:192
	v_bfe_u32 v2, v54, 16, 1
	v_add3_u32 v2, v54, v2, s72
	ds_write_b16_d16_hi v61, v2 offset:192
	v_bfe_u32 v2, v45, 16, 1
	v_add3_u32 v2, v45, v2, s72
	ds_write_b16_d16_hi v42, v2 offset:224
	v_bfe_u32 v2, v47, 16, 1
	v_add3_u32 v2, v47, v2, s72
	ds_write_b16_d16_hi v59, v2 offset:224
	v_bfe_u32 v2, v36, 16, 1
	v_add3_u32 v2, v36, v2, s72
	ds_write_b16_d16_hi v60, v2 offset:224
	v_bfe_u32 v2, v33, 16, 1
	v_add3_u32 v2, v33, v2, s72
	ds_write_b16_d16_hi v61, v2 offset:224
	v_bfe_u32 v2, v44, 16, 1
	v_add3_u32 v2, v44, v2, s72
	ds_write_b16_d16_hi v42, v2 offset:256
	v_bfe_u32 v2, v35, 16, 1
	v_add3_u32 v2, v35, v2, s72
	ds_write_b16_d16_hi v59, v2 offset:256
	v_bfe_u32 v2, v20, 16, 1
	v_add3_u32 v2, v20, v2, s72
	ds_write_b16_d16_hi v60, v2 offset:256
	v_bfe_u32 v2, v37, 16, 1
	v_add3_u32 v2, v37, v2, s72
	v_mul_u32_u24_e32 v3, 0x150, v43
	ds_write_b16_d16_hi v61, v2 offset:256
	v_add3_u32 v2, v57, v41, v39
	ds_write_b16 v2, v1 offset:288
	v_add3_u32 v2, v57, v3, v39
	ds_write_b16 v2, v1 offset:288
	v_add3_u32 v2, v57, v4, v39
	v_lshl_add_u32 v45, v56, 3, v58
	s_movk_i32 s0, 0x100
	ds_write_b16 v2, v1 offset:288
	v_add3_u32 v2, v57, v5, v39
	v_and_b32_e32 v46, 8, v50
	v_cmp_gt_i32_e32 vcc, s0, v45
	ds_write_b16 v2, v1 offset:288
	v_mul_u32_u24_e32 v2, 0x150, v55
	v_cndmask_b32_e32 v30, 0, v46, vcc
	s_waitcnt lgkmcnt(0)
	v_add3_u32 v2, v57, v2, v52
	v_mad_u32_u24 v47, v55, s25, 0
	v_xor_b32_e32 v30, v30, v45
	ds_read_b128 v[18:21], v2
	ds_read_b128 v[14:17], v2 offset:64
	ds_read_b128 v[10:13], v2 offset:128
	ds_read_b128 v[6:9], v2 offset:192
	ds_read_b128 v[2:5], v2 offset:256
	s_waitcnt lgkmcnt(0)
	v_lshl_add_u32 v30, v30, 1, v47
	s_movk_i32 s0, 0xe0
	ds_read_b128 v[30:33], v30
	v_cmp_gt_i32_e64 s[0:1], s0, v45
	v_add_u32_e32 v48, 32, v45
	v_cmp_gt_i32_e64 s[38:39], s2, v45
	v_cndmask_b32_e64 v34, 0, v46, s[0:1]
	v_xor_b32_e32 v34, v34, v48
	v_lshl_add_u32 v34, v34, 1, v47
	ds_read_b128 v[34:37], v34
	s_waitcnt lgkmcnt(1)
	v_mfma_f32_16x16x32_bf16 v[30:33], v[18:21], v[30:33], 0
	v_add_u32_e32 v49, 64, v45
	s_movk_i32 s2, 0xa0
	v_cmp_gt_i32_e64 s[40:41], s2, v45
	s_waitcnt lgkmcnt(0)
	v_mfma_f32_16x16x32_bf16 v[30:33], v[14:17], v[34:37], v[30:33]
	v_cndmask_b32_e64 v34, 0, v46, s[38:39]
	v_xor_b32_e32 v34, v34, v49
	v_lshl_add_u32 v34, v34, 1, v47
	ds_read_b128 v[34:37], v34
	v_add_u32_e32 v50, 0x60, v45
	s_waitcnt lgkmcnt(0)
	v_mfma_f32_16x16x32_bf16 v[30:33], v[10:13], v[34:37], v[30:33]
	v_cndmask_b32_e64 v34, 0, v46, s[40:41]
	v_xor_b32_e32 v34, v34, v50
	v_lshl_add_u32 v34, v34, 1, v47
	ds_read_b128 v[34:37], v34
	s_movk_i32 s2, 0x80
	v_cmp_gt_i32_e64 s[42:43], s2, v45
	s_waitcnt lgkmcnt(0)
; __device__ __forceinline__ float frcp(float x) { return __builtin_amdgcn_rcpf(x); }
; __device__ void swa_item(const Params& p, int item) {
;     ...
;   _Pragma("unroll") for (int jj = 0; jj < 4; ++jj) il[jj] = frcp(ls[jj]);
;   bfu* Ow = Pl;
;   _Pragma("unroll") for (int dt = 0; dt < 8; ++dt) {
;     f32x4 a = (f32x4){0.f, 0.f, 0.f, 0.f};
;     _Pragma("unroll") for (int kk = 0; kk < 5; ++kk) {
;       const int k0_ = w * 16 + kk * 32 + q * 8; const int ch_ = k0_ >> 3;
;       const int chp_ = (ch_ < 32) ? (ch_ ^ (((dt * 16 + c) >> 3) & 15)) : ch_;
;       bf16x8 vf = *(const bf16x8*)(Vt + (dt * 16 + c) * 280 + chp_ * 8);
;       a = __builtin_amdgcn_mfma_f32_16x16x32_bf16(pf[kk], vf, a, 0, 0, 0);
;     }
;     _Pragma("unroll") for (int jj = 0; jj < 4; ++jj) Ow[(q * 4 + jj) * 136 + dt * 16 + c] = f2bf(a[jj] * il[jj]);
;   }
	v_mfma_f32_16x16x32_bf16 v[30:33], v[6:9], v[34:37], v[30:33]
	v_add_u32_e32 v52, 0x80, v45
	v_cndmask_b32_e64 v34, 0, v46, s[42:43]
	v_xor_b32_e32 v34, v34, v52
	v_lshl_add_u32 v34, v34, 1, v47
	ds_read_b128 v[34:37], v34
	v_rcp_f32_e32 v39, v26
	s_waitcnt lgkmcnt(0)
	v_mfma_f32_16x16x32_bf16 v[30:33], v[2:5], v[34:37], v[30:33]
	v_rcp_f32_e32 v41, v27
	s_movk_i32 s2, 0x440
	v_rcp_f32_e32 v42, v28
	s_nop 4
	v_mul_f32_e32 v30, v39, v30
	v_bfe_u32 v34, v30, 16, 1
	v_add3_u32 v30, v30, v34, s72
	v_mad_u32_u24 v53, v56, s2, v40
	ds_write_b16_d16_hi v53, v30
	v_mul_f32_e32 v30, v41, v31
	v_bfe_u32 v31, v30, 16, 1
	v_rcp_f32_e32 v44, v29
	v_add3_u32 v30, v30, v31, s72
	v_mad_u32_u24 v40, v43, s3, v40
	ds_write_b16_d16_hi v40, v30
	v_mul_f32_e32 v30, v42, v32
	v_bfe_u32 v31, v30, 16, 1
	v_add3_u32 v30, v30, v31, s72
	ds_write_b16_d16_hi v40, v30 offset:272
	v_mul_f32_e32 v30, v44, v33
	v_bfe_u32 v31, v30, 16, 1
	v_add3_u32 v30, v30, v31, s72
	v_or_b32_e32 v43, 16, v46
	ds_write_b16_d16_hi v40, v30 offset:544
	v_cndmask_b32_e32 v30, 0, v43, vcc
	v_xor_b32_e32 v30, v30, v45
	v_lshl_add_u32 v30, v30, 1, v47
	ds_read_b128 v[30:33], v30 offset:8960
	v_cndmask_b32_e64 v34, 0, v43, s[0:1]
	v_xor_b32_e32 v34, v34, v48
	v_lshl_add_u32 v34, v34, 1, v47
	ds_read_b128 v[34:37], v34 offset:8960
	s_waitcnt lgkmcnt(1)
	v_mfma_f32_16x16x32_bf16 v[30:33], v[18:21], v[30:33], 0
	s_waitcnt lgkmcnt(0)
	v_mfma_f32_16x16x32_bf16 v[30:33], v[14:17], v[34:37], v[30:33]
	v_cndmask_b32_e64 v34, 0, v43, s[38:39]
	v_xor_b32_e32 v34, v34, v49
	v_lshl_add_u32 v34, v34, 1, v47
	ds_read_b128 v[34:37], v34 offset:8960
	s_waitcnt lgkmcnt(0)
	v_mfma_f32_16x16x32_bf16 v[30:33], v[10:13], v[34:37], v[30:33]
	v_cndmask_b32_e64 v34, 0, v43, s[40:41]
	v_xor_b32_e32 v34, v34, v50
	v_lshl_add_u32 v34, v34, 1, v47
	ds_read_b128 v[34:37], v34 offset:8960
	s_waitcnt lgkmcnt(0)
	v_mfma_f32_16x16x32_bf16 v[30:33], v[6:9], v[34:37], v[30:33]
	v_cndmask_b32_e64 v34, 0, v43, s[42:43]
	v_xor_b32_e32 v34, v34, v52
	v_lshl_add_u32 v34, v34, 1, v47
	ds_read_b128 v[34:37], v34 offset:8960
	v_or_b32_e32 v43, 32, v46
	s_waitcnt lgkmcnt(0)
	v_mfma_f32_16x16x32_bf16 v[30:33], v[2:5], v[34:37], v[30:33]
	s_nop 7
	v_mul_f32_e32 v30, v39, v30
	v_bfe_u32 v34, v30, 16, 1
	v_add3_u32 v30, v30, v34, s72
	ds_write_b16_d16_hi v53, v30 offset:32
	v_mul_f32_e32 v30, v41, v31
	v_bfe_u32 v31, v30, 16, 1
	v_add3_u32 v30, v30, v31, s72
	ds_write_b16_d16_hi v40, v30 offset:32
	v_mul_f32_e32 v30, v42, v32
	v_bfe_u32 v31, v30, 16, 1
	v_add3_u32 v30, v30, v31, s72
	ds_write_b16_d16_hi v40, v30 offset:304
	v_mul_f32_e32 v30, v44, v33
	v_bfe_u32 v31, v30, 16, 1
	v_add3_u32 v30, v30, v31, s72
	ds_write_b16_d16_hi v40, v30 offset:576
	v_cndmask_b32_e32 v30, 0, v43, vcc
	v_xor_b32_e32 v30, v30, v45
	v_lshl_add_u32 v30, v30, 1, v47
	ds_read_b128 v[30:33], v30 offset:17920
	v_cndmask_b32_e64 v34, 0, v43, s[0:1]
	v_xor_b32_e32 v34, v34, v48
	v_lshl_add_u32 v34, v34, 1, v47
	ds_read_b128 v[34:37], v34 offset:17920
	s_waitcnt lgkmcnt(1)
	v_mfma_f32_16x16x32_bf16 v[30:33], v[18:21], v[30:33], 0
	s_waitcnt lgkmcnt(0)
	v_mfma_f32_16x16x32_bf16 v[30:33], v[14:17], v[34:37], v[30:33]
	v_cndmask_b32_e64 v34, 0, v43, s[38:39]
	v_xor_b32_e32 v34, v34, v49
	v_lshl_add_u32 v34, v34, 1, v47
	ds_read_b128 v[34:37], v34 offset:17920
	s_waitcnt lgkmcnt(0)
	v_mfma_f32_16x16x32_bf16 v[30:33], v[10:13], v[34:37], v[30:33]
	v_cndmask_b32_e64 v34, 0, v43, s[40:41]
	v_xor_b32_e32 v34, v34, v50
	v_lshl_add_u32 v34, v34, 1, v47
	ds_read_b128 v[34:37], v34 offset:17920
	s_waitcnt lgkmcnt(0)
	v_mfma_f32_16x16x32_bf16 v[30:33], v[6:9], v[34:37], v[30:33]
	v_cndmask_b32_e64 v34, 0, v43, s[42:43]
	v_xor_b32_e32 v34, v34, v52
	v_lshl_add_u32 v34, v34, 1, v47
	ds_read_b128 v[34:37], v34 offset:17920
	v_or_b32_e32 v43, 48, v46
	s_waitcnt lgkmcnt(0)
	v_mfma_f32_16x16x32_bf16 v[30:33], v[2:5], v[34:37], v[30:33]
	s_nop 7
	v_mul_f32_e32 v30, v39, v30
	v_bfe_u32 v34, v30, 16, 1
	v_add3_u32 v30, v30, v34, s72
	ds_write_b16_d16_hi v53, v30 offset:64
	v_mul_f32_e32 v30, v41, v31
	v_bfe_u32 v31, v30, 16, 1
	v_add3_u32 v30, v30, v31, s72
	ds_write_b16_d16_hi v40, v30 offset:64
	v_mul_f32_e32 v30, v42, v32
	v_bfe_u32 v31, v30, 16, 1
	v_add3_u32 v30, v30, v31, s72
	ds_write_b16_d16_hi v40, v30 offset:336
	v_mul_f32_e32 v30, v44, v33
	v_bfe_u32 v31, v30, 16, 1
	v_add3_u32 v30, v30, v31, s72
	ds_write_b16_d16_hi v40, v30 offset:608
	v_cndmask_b32_e32 v30, 0, v43, vcc
	v_xor_b32_e32 v30, v30, v45
	v_lshl_add_u32 v30, v30, 1, v47
	ds_read_b128 v[30:33], v30 offset:26880
	v_cndmask_b32_e64 v34, 0, v43, s[0:1]
	v_xor_b32_e32 v34, v34, v48
	v_lshl_add_u32 v34, v34, 1, v47
	ds_read_b128 v[34:37], v34 offset:26880
	s_waitcnt lgkmcnt(1)
	v_mfma_f32_16x16x32_bf16 v[30:33], v[18:21], v[30:33], 0
	s_waitcnt lgkmcnt(0)
	v_mfma_f32_16x16x32_bf16 v[30:33], v[14:17], v[34:37], v[30:33]
	v_cndmask_b32_e64 v34, 0, v43, s[38:39]
	v_xor_b32_e32 v34, v34, v49
	v_lshl_add_u32 v34, v34, 1, v47
	ds_read_b128 v[34:37], v34 offset:26880
	s_waitcnt lgkmcnt(0)
	v_mfma_f32_16x16x32_bf16 v[30:33], v[10:13], v[34:37], v[30:33]
	v_cndmask_b32_e64 v34, 0, v43, s[40:41]
	v_xor_b32_e32 v34, v34, v50
	v_lshl_add_u32 v34, v34, 1, v47
	ds_read_b128 v[34:37], v34 offset:26880
	s_waitcnt lgkmcnt(0)
	v_mfma_f32_16x16x32_bf16 v[30:33], v[6:9], v[34:37], v[30:33]
	v_cndmask_b32_e64 v34, 0, v43, s[42:43]
	v_xor_b32_e32 v34, v34, v52
	v_lshl_add_u32 v34, v34, 1, v47
	ds_read_b128 v[34:37], v34 offset:26880
	v_or_b32_e32 v43, 64, v46
	s_waitcnt lgkmcnt(0)
; __device__ void swa_item(const Params& p, int item) {
;     ...
;   _Pragma("unroll") for (int dt = 0; dt < 8; ++dt) {
;     f32x4 a = (f32x4){0.f, 0.f, 0.f, 0.f};
;     _Pragma("unroll") for (int kk = 0; kk < 5; ++kk) {
;       const int k0_ = w * 16 + kk * 32 + q * 8; const int ch_ = k0_ >> 3;
;       const int chp_ = (ch_ < 32) ? (ch_ ^ (((dt * 16 + c) >> 3) & 15)) : ch_;
;       bf16x8 vf = *(const bf16x8*)(Vt + (dt * 16 + c) * 280 + chp_ * 8);
;       a = __builtin_amdgcn_mfma_f32_16x16x32_bf16(pf[kk], vf, a, 0, 0, 0);
;     }
;     _Pragma("unroll") for (int jj = 0; jj < 4; ++jj) Ow[(q * 4 + jj) * 136 + dt * 16 + c] = f2bf(a[jj] * il[jj]);
;   }
	v_mfma_f32_16x16x32_bf16 v[30:33], v[2:5], v[34:37], v[30:33]
	s_nop 7
	v_mul_f32_e32 v30, v39, v30
	v_bfe_u32 v34, v30, 16, 1
	v_add3_u32 v30, v30, v34, s72
	ds_write_b16_d16_hi v53, v30 offset:96
	v_mul_f32_e32 v30, v41, v31
	v_bfe_u32 v31, v30, 16, 1
	v_add3_u32 v30, v30, v31, s72
	ds_write_b16_d16_hi v40, v30 offset:96
	v_mul_f32_e32 v30, v42, v32
	v_bfe_u32 v31, v30, 16, 1
	v_add3_u32 v30, v30, v31, s72
	ds_write_b16_d16_hi v40, v30 offset:368
	v_mul_f32_e32 v30, v44, v33
	v_bfe_u32 v31, v30, 16, 1
	v_add3_u32 v30, v30, v31, s72
	ds_write_b16_d16_hi v40, v30 offset:640
	v_cndmask_b32_e32 v30, 0, v43, vcc
	v_xor_b32_e32 v30, v30, v45
	v_lshl_add_u32 v30, v30, 1, v47
	ds_read_b128 v[30:33], v30 offset:35840
	v_cndmask_b32_e64 v34, 0, v43, s[0:1]
	v_xor_b32_e32 v34, v34, v48
	v_lshl_add_u32 v34, v34, 1, v47
	ds_read_b128 v[34:37], v34 offset:35840
	s_waitcnt lgkmcnt(1)
	v_mfma_f32_16x16x32_bf16 v[30:33], v[18:21], v[30:33], 0
	s_waitcnt lgkmcnt(0)
	v_mfma_f32_16x16x32_bf16 v[30:33], v[14:17], v[34:37], v[30:33]
	v_cndmask_b32_e64 v34, 0, v43, s[38:39]
	v_xor_b32_e32 v34, v34, v49
	v_lshl_add_u32 v34, v34, 1, v47
	ds_read_b128 v[34:37], v34 offset:35840
	s_waitcnt lgkmcnt(0)
	v_mfma_f32_16x16x32_bf16 v[30:33], v[10:13], v[34:37], v[30:33]
	v_cndmask_b32_e64 v34, 0, v43, s[40:41]
	v_xor_b32_e32 v34, v34, v50
	v_lshl_add_u32 v34, v34, 1, v47
	ds_read_b128 v[34:37], v34 offset:35840
	s_waitcnt lgkmcnt(0)
	v_mfma_f32_16x16x32_bf16 v[30:33], v[6:9], v[34:37], v[30:33]
	v_cndmask_b32_e64 v34, 0, v43, s[42:43]
	v_xor_b32_e32 v34, v34, v52
	v_lshl_add_u32 v34, v34, 1, v47
	ds_read_b128 v[34:37], v34 offset:35840
	v_or_b32_e32 v43, 0x50, v46
	s_waitcnt lgkmcnt(0)
	v_mfma_f32_16x16x32_bf16 v[30:33], v[2:5], v[34:37], v[30:33]
	s_nop 7
	v_mul_f32_e32 v30, v39, v30
	v_bfe_u32 v34, v30, 16, 1
	v_add3_u32 v30, v30, v34, s72
	ds_write_b16_d16_hi v53, v30 offset:128
	v_mul_f32_e32 v30, v41, v31
	v_bfe_u32 v31, v30, 16, 1
	v_add3_u32 v30, v30, v31, s72
	ds_write_b16_d16_hi v40, v30 offset:128
	v_mul_f32_e32 v30, v42, v32
	v_bfe_u32 v31, v30, 16, 1
	v_add3_u32 v30, v30, v31, s72
	ds_write_b16_d16_hi v40, v30 offset:400
	v_mul_f32_e32 v30, v44, v33
	v_bfe_u32 v31, v30, 16, 1
	v_add3_u32 v30, v30, v31, s72
	ds_write_b16_d16_hi v40, v30 offset:672
	v_cndmask_b32_e32 v30, 0, v43, vcc
	v_xor_b32_e32 v30, v30, v45
	v_lshl_add_u32 v30, v30, 1, v47
	ds_read_b128 v[30:33], v30 offset:44800
	v_cndmask_b32_e64 v34, 0, v43, s[0:1]
	v_xor_b32_e32 v34, v34, v48
	v_lshl_add_u32 v34, v34, 1, v47
	ds_read_b128 v[34:37], v34 offset:44800
	s_waitcnt lgkmcnt(1)
	v_mfma_f32_16x16x32_bf16 v[30:33], v[18:21], v[30:33], 0
	s_waitcnt lgkmcnt(0)
	v_mfma_f32_16x16x32_bf16 v[30:33], v[14:17], v[34:37], v[30:33]
	v_cndmask_b32_e64 v34, 0, v43, s[38:39]
	v_xor_b32_e32 v34, v34, v49
	v_lshl_add_u32 v34, v34, 1, v47
	ds_read_b128 v[34:37], v34 offset:44800
	s_waitcnt lgkmcnt(0)
	v_mfma_f32_16x16x32_bf16 v[30:33], v[10:13], v[34:37], v[30:33]
	v_cndmask_b32_e64 v34, 0, v43, s[40:41]
	v_xor_b32_e32 v34, v34, v50
	v_lshl_add_u32 v34, v34, 1, v47
	ds_read_b128 v[34:37], v34 offset:44800
	s_waitcnt lgkmcnt(0)
	v_mfma_f32_16x16x32_bf16 v[30:33], v[6:9], v[34:37], v[30:33]
	v_cndmask_b32_e64 v34, 0, v43, s[42:43]
	v_xor_b32_e32 v34, v34, v52
	v_lshl_add_u32 v34, v34, 1, v47
	ds_read_b128 v[34:37], v34 offset:44800
	v_or_b32_e32 v43, 0x60, v46
	s_waitcnt lgkmcnt(0)
	v_mfma_f32_16x16x32_bf16 v[30:33], v[2:5], v[34:37], v[30:33]
	s_nop 7
	v_mul_f32_e32 v30, v39, v30
	v_bfe_u32 v34, v30, 16, 1
	v_add3_u32 v30, v30, v34, s72
	ds_write_b16_d16_hi v53, v30 offset:160
	v_mul_f32_e32 v30, v41, v31
	v_bfe_u32 v31, v30, 16, 1
	v_add3_u32 v30, v30, v31, s72
	ds_write_b16_d16_hi v40, v30 offset:160
	v_mul_f32_e32 v30, v42, v32
	v_bfe_u32 v31, v30, 16, 1
	v_add3_u32 v30, v30, v31, s72
	ds_write_b16_d16_hi v40, v30 offset:432
	v_mul_f32_e32 v30, v44, v33
	v_bfe_u32 v31, v30, 16, 1
	v_add3_u32 v30, v30, v31, s72
	ds_write_b16_d16_hi v40, v30 offset:704
	v_cndmask_b32_e32 v30, 0, v43, vcc
	v_xor_b32_e32 v30, v30, v45
	v_lshl_add_u32 v30, v30, 1, v47
	ds_read_b128 v[30:33], v30 offset:53760
	v_cndmask_b32_e64 v34, 0, v43, s[0:1]
	v_xor_b32_e32 v34, v34, v48
	v_lshl_add_u32 v34, v34, 1, v47
	ds_read_b128 v[34:37], v34 offset:53760
	s_waitcnt lgkmcnt(1)
	v_mfma_f32_16x16x32_bf16 v[30:33], v[18:21], v[30:33], 0
	s_waitcnt lgkmcnt(0)
	v_mfma_f32_16x16x32_bf16 v[30:33], v[14:17], v[34:37], v[30:33]
	v_cndmask_b32_e64 v34, 0, v43, s[38:39]
	v_xor_b32_e32 v34, v34, v49
	v_lshl_add_u32 v34, v34, 1, v47
	ds_read_b128 v[34:37], v34 offset:53760
	s_waitcnt lgkmcnt(0)
	v_mfma_f32_16x16x32_bf16 v[30:33], v[10:13], v[34:37], v[30:33]
	v_cndmask_b32_e64 v34, 0, v43, s[40:41]
	v_xor_b32_e32 v34, v34, v50
	v_lshl_add_u32 v34, v34, 1, v47
	ds_read_b128 v[34:37], v34 offset:53760
	s_waitcnt lgkmcnt(0)
	v_mfma_f32_16x16x32_bf16 v[30:33], v[6:9], v[34:37], v[30:33]
	v_cndmask_b32_e64 v34, 0, v43, s[42:43]
	v_xor_b32_e32 v34, v34, v52
	v_lshl_add_u32 v34, v34, 1, v47
	ds_read_b128 v[34:37], v34 offset:53760
	s_waitcnt lgkmcnt(0)
; __device__ __forceinline__ float flog(float x) { return __builtin_amdgcn_logf(x) * 0.6931471805599453f; }
; __device__ void swa_item(const Params& p, int item) {
;     ...
;   _Pragma("unroll") for (int dt = 0; dt < 8; ++dt) {
;     f32x4 a = (f32x4){0.f, 0.f, 0.f, 0.f};
;     _Pragma("unroll") for (int kk = 0; kk < 5; ++kk) {
;       const int k0_ = w * 16 + kk * 32 + q * 8; const int ch_ = k0_ >> 3;
;       const int chp_ = (ch_ < 32) ? (ch_ ^ (((dt * 16 + c) >> 3) & 15)) : ch_;
;       bf16x8 vf = *(const bf16x8*)(Vt + (dt * 16 + c) * 280 + chp_ * 8);
;       a = __builtin_amdgcn_mfma_f32_16x16x32_bf16(pf[kk], vf, a, 0, 0, 0);
;     }
;     _Pragma("unroll") for (int jj = 0; jj < 4; ++jj) Ow[(q * 4 + jj) * 136 + dt * 16 + c] = f2bf(a[jj] * il[jj]);
;   }
;   asm volatile("s_waitcnt lgkmcnt(0)" ::: "memory");
;   _Pragma("unroll") for (int i = 0; i < 4; ++i) {
;     const int id = lane + 64 * i; const int rr = id >> 4, c8 = id & 15;
;     long orow = rowb + (long)(qb * 128 + w * 16 + rr) * dil + r;
;     *(bf16x8*)(buf + orow * 4608 + qcol + c8 * 8) = *(const bf16x8*)(Ow + rr * 136 + c8 * 8);
;   }
;   if (c == 0) {
;     _Pragma("unroll") for (int jj = 0; jj < 4; ++jj) {
;       long orow = rowb + (long)(qb * 128 + w * 16 + q * 4 + jj) * dil + r;
;       misc[MF_LSE + ((long)pat * MTOK + orow) * 4 + head] = mx[jj] + flog(ls[jj]);
;     }
;   }
	v_mfma_f32_16x16x32_bf16 v[30:33], v[2:5], v[34:37], v[30:33]
	s_nop 7
	v_mul_f32_e32 v30, v39, v30
	v_bfe_u32 v34, v30, 16, 1
	v_add3_u32 v30, v30, v34, s72
	ds_write_b16_d16_hi v53, v30 offset:192
	v_mul_f32_e32 v30, v41, v31
	v_bfe_u32 v31, v30, 16, 1
	v_add3_u32 v30, v30, v31, s72
	ds_write_b16_d16_hi v40, v30 offset:192
	v_mul_f32_e32 v30, v42, v32
	v_bfe_u32 v31, v30, 16, 1
	v_add3_u32 v30, v30, v31, s72
	ds_write_b16_d16_hi v40, v30 offset:464
	v_mul_f32_e32 v30, v44, v33
	v_bfe_u32 v31, v30, 16, 1
	v_add3_u32 v30, v30, v31, s72
	v_or_b32_e32 v34, 0x70, v46
	ds_write_b16_d16_hi v40, v30 offset:736
	v_cndmask_b32_e32 v30, 0, v34, vcc
	v_xor_b32_e32 v30, v30, v45
	v_lshl_add_u32 v30, v30, 1, v47
	ds_read_b128 v[30:33], v30 offset:62720
	v_cmp_eq_u32_e32 vcc, 0, v55
	s_waitcnt lgkmcnt(0)
	v_mfma_f32_16x16x32_bf16 v[18:21], v[18:21], v[30:33], 0
	v_cndmask_b32_e64 v30, 0, v34, s[0:1]
	v_xor_b32_e32 v30, v30, v48
	v_lshl_add_u32 v30, v30, 1, v47
	ds_read_b128 v[30:33], v30 offset:62720
	s_waitcnt lgkmcnt(0)
	v_mfma_f32_16x16x32_bf16 v[14:17], v[14:17], v[30:33], v[18:21]
	s_nop 2
	v_cndmask_b32_e64 v18, 0, v34, s[38:39]
	v_xor_b32_e32 v18, v18, v49
	v_lshl_add_u32 v18, v18, 1, v47
	ds_read_b128 v[18:21], v18 offset:62720
	s_waitcnt lgkmcnt(0)
	v_mfma_f32_16x16x32_bf16 v[10:13], v[10:13], v[18:21], v[14:17]
	s_nop 2
	v_cndmask_b32_e64 v14, 0, v34, s[40:41]
	v_xor_b32_e32 v14, v14, v50
	v_lshl_add_u32 v14, v14, 1, v47
	ds_read_b128 v[14:17], v14 offset:62720
	s_waitcnt lgkmcnt(0)
	v_mfma_f32_16x16x32_bf16 v[6:9], v[6:9], v[14:17], v[10:13]
	s_nop 2
	v_cndmask_b32_e64 v10, 0, v34, s[42:43]
	v_xor_b32_e32 v10, v10, v52
	v_lshl_add_u32 v10, v10, 1, v47
	ds_read_b128 v[10:13], v10 offset:62720
	s_waitcnt lgkmcnt(0)
	v_mfma_f32_16x16x32_bf16 v[2:5], v[2:5], v[10:13], v[6:9]
	s_nop 2
	v_or_b32_e32 v8, v51, v56
	v_ashrrev_i32_e32 v9, 31, v8
	s_nop 2
	v_mul_f32_e32 v2, v39, v2
	v_bfe_u32 v6, v2, 16, 1
	v_add3_u32 v2, v2, v6, s72
	ds_write_b16_d16_hi v53, v2 offset:224
	v_mul_f32_e32 v2, v41, v3
	v_bfe_u32 v3, v2, 16, 1
	v_add3_u32 v2, v2, v3, s72
	ds_write_b16_d16_hi v40, v2 offset:224
	v_mul_f32_e32 v2, v42, v4
	v_bfe_u32 v3, v2, 16, 1
	v_add3_u32 v2, v2, v3, s72
	ds_write_b16_d16_hi v40, v2 offset:496
	v_mul_f32_e32 v2, v44, v5
	v_bfe_u32 v3, v2, 16, 1
	v_add3_u32 v2, v2, v3, s72
	ds_write_b16_d16_hi v40, v2 offset:768
	v_lshlrev_b64 v[2:3], s22, v[8:9]
	v_lshl_add_u64 v[10:11], v[2:3], 0, s[26:27]
	v_mul_u32_u24_e32 v2, 0x110, v56
	s_waitcnt lgkmcnt(0)
	v_lshl_add_u64 v[6:7], s[52:53], 0, v[0:1]
	v_add3_u32 v0, v57, v0, v2
	ds_read_b128 v[2:5], v0
	v_mad_u64_u32 v[12:13], s[0:1], v10, s89, v[6:7]
	v_mad_i32_i24 v13, v11, s89, v13
	s_waitcnt lgkmcnt(0)
	global_store_dwordx4 v[12:13], v[2:5], off
	s_nop 1
	v_or_b32_e32 v2, 4, v8
	v_ashrrev_i32_e32 v3, 31, v2
	v_lshlrev_b64 v[2:3], s22, v[2:3]
	v_lshl_add_u64 v[10:11], v[2:3], 0, s[26:27]
	ds_read_b128 v[2:5], v0 offset:1088
	v_mad_u64_u32 v[12:13], s[0:1], v10, s89, v[6:7]
	v_mad_i32_i24 v13, v11, s89, v13
	s_waitcnt lgkmcnt(0)
	global_store_dwordx4 v[12:13], v[2:5], off
	s_nop 1
	v_or_b32_e32 v2, 8, v8
	v_ashrrev_i32_e32 v3, 31, v2
	v_lshlrev_b64 v[2:3], s22, v[2:3]
	v_lshl_add_u64 v[10:11], v[2:3], 0, s[26:27]
	ds_read_b128 v[2:5], v0 offset:2176
	v_mad_u64_u32 v[12:13], s[0:1], v10, s89, v[6:7]
	v_mad_i32_i24 v13, v11, s89, v13
	s_waitcnt lgkmcnt(0)
	global_store_dwordx4 v[12:13], v[2:5], off
	s_nop 1
	v_or_b32_e32 v2, 12, v8
	v_ashrrev_i32_e32 v3, 31, v2
	v_lshlrev_b64 v[2:3], s22, v[2:3]
	v_lshl_add_u64 v[8:9], v[2:3], 0, s[26:27]
	ds_read_b128 v[2:5], v0 offset:3264
	v_mad_u64_u32 v[6:7], s[0:1], v8, s89, v[6:7]
	v_mad_i32_i24 v7, v9, s89, v7
	s_waitcnt lgkmcnt(0)
	global_store_dwordx4 v[6:7], v[2:5], off
	s_and_saveexec_b64 s[0:1], vcc
	s_cbranch_execz .LBB0_101
	s_ashr_i32 s89, s88, 31
	s_lshl_b64 s[2:3], s[88:89], 19
	v_readlane_b32 s12, v252, 20
	v_log_f32_e32 v0, v26
	s_add_u32 s2, s12, s2
	v_readlane_b32 s12, v252, 21
	v_or_b32_e32 v2, v51, v38
	s_addc_u32 s3, s12, s3
	s_lshl_b32 s12, s23, 2
	s_add_u32 s2, s2, s12
	v_ashrrev_i32_e32 v3, 31, v2
	v_readlane_b32 s12, v254, 13
	v_lshlrev_b64 v[4:5], s22, v[2:3]
	v_readlane_b32 s13, v254, 14
	v_fmac_f32_e32 v22, 0x3f317218, v0
	v_log_f32_e32 v0, v27
	s_addc_u32 s3, s3, 0
	v_lshl_add_u64 v[4:5], v[4:5], 0, s[12:13]
	v_lshl_add_u64 v[4:5], v[4:5], 4, s[2:3]
	global_store_dword v[4:5], v22, off
	v_or_b32_e32 v4, 1, v2
	v_ashrrev_i32_e32 v5, 31, v4
	v_fmac_f32_e32 v23, 0x3f317218, v0
	v_log_f32_e32 v0, v28
	v_lshlrev_b64 v[4:5], s22, v[4:5]
	v_lshl_add_u64 v[4:5], v[4:5], 0, s[12:13]
	v_lshl_add_u64 v[4:5], v[4:5], 4, s[2:3]
	global_store_dword v[4:5], v23, off
	v_or_b32_e32 v4, 2, v2
	v_fmac_f32_e32 v24, 0x3f317218, v0
	v_or_b32_e32 v2, 3, v2
	v_log_f32_e32 v0, v29
	v_ashrrev_i32_e32 v5, 31, v4
	v_ashrrev_i32_e32 v3, 31, v2
	v_lshlrev_b64 v[4:5], s22, v[4:5]
	v_lshlrev_b64 v[2:3], s22, v[2:3]
	v_lshl_add_u64 v[4:5], v[4:5], 0, s[12:13]
	v_lshl_add_u64 v[2:3], v[2:3], 0, s[12:13]
	s_movk_i32 s89, 0x2400
	v_lshl_add_u64 v[4:5], v[4:5], 4, s[2:3]
	v_fmac_f32_e32 v25, 0x3f317218, v0
	v_lshl_add_u64 v[2:3], v[2:3], 4, s[2:3]
	global_store_dword v[4:5], v24, off
	global_store_dword v[2:3], v25, off
	s_branch .LBB0_101
